# MFMA order: per (m,n) the bj0 pair then bj1 pair, each pair = same accumulator k0,k1 back-to-back; A-fragment operand reused by every other MFMA for 8 MFMAs
# speedup vs baseline: 1.0198x; 1.0133x over previous
.LBB0_147:
	s_sleep 2
	s_add_u32 s42, s40, 0xfff80080
	s_addc_u32 s43, s41, -1
	s_add_i32 s71, 0, 0x10000
	s_cmp_eq_u32 s63, 28
	s_cselect_b32 s45, s2, s43
	s_cselect_b32 s44, s5, s42
	s_cselect_b32 s43, s23, s62
	s_cselect_b32 s42, s25, s31
	s_add_i32 s73, 0, 0x14000
	s_waitcnt lgkmcnt(0)
	v_add_u32_e32 v156, s71, v169
	v_add_u32_e32 v178, s73, v169
	ds_read_b128 v[132:135], v156
	ds_read_b128 v[136:139], v156 offset:1024
	ds_read_b128 v[152:155], v156 offset:2048
	ds_read_b128 v[156:159], v156 offset:3072
	ds_read_b128 v[160:163], v178
	ds_read_b128 v[164:167], v178 offset:1024
	ds_read_b128 v[174:177], v178 offset:2048
	ds_read_b128 v[178:181], v178 offset:3072
	v_lshl_add_u64 v[202:203], s[40:41], 0, v[148:149]
	s_add_i32 m0, s53, 0xc000
	ds_read_b128 v[182:185], v171
	ds_read_b128 v[186:189], v171 offset:1024
	ds_read_b128 v[190:193], v171 offset:2048
	ds_read_b128 v[194:197], v171 offset:3072
	ds_read_b128 v[198:201], v171 offset:4096
	ds_read_b128 v[208:211], v171 offset:5120
	ds_read_b128 v[212:215], v171 offset:6144
	ds_read_b128 v[216:219], v171 offset:7168
	global_load_lds_dwordx4 v[202:203], off
	v_lshl_add_u64 v[202:203], s[40:41], 0, v[150:151]
	s_add_i32 m0, s53, 0xe000
	s_nop 0
	global_load_lds_dwordx4 v[202:203], off
	s_waitcnt vmcnt(8)
	s_waitcnt lgkmcnt(0)
	s_barrier
	s_setprio 1
	s_waitcnt lgkmcnt(0)
	v_mfma_f32_16x16x32_bf16 v[128:131], v[132:135], v[182:185], v[128:131]
	v_mfma_f32_16x16x32_bf16 v[128:131], v[136:139], v[186:189], v[128:131]
	v_mfma_f32_16x16x32_bf16 v[116:119], v[160:163], v[182:185], v[116:119]
	v_mfma_f32_16x16x32_bf16 v[116:119], v[164:167], v[186:189], v[116:119]
	v_mfma_f32_16x16x32_bf16 v[124:127], v[152:155], v[182:185], v[124:127]
	v_mfma_f32_16x16x32_bf16 v[124:127], v[156:159], v[186:189], v[124:127]
	v_mfma_f32_16x16x32_bf16 v[108:111], v[174:177], v[182:185], v[108:111]
	v_mfma_f32_16x16x32_bf16 v[108:111], v[178:181], v[186:189], v[108:111]
	v_mfma_f32_16x16x32_bf16 v[120:123], v[132:135], v[190:193], v[120:123]
	v_mfma_f32_16x16x32_bf16 v[120:123], v[136:139], v[194:197], v[120:123]
	v_mfma_f32_16x16x32_bf16 v[100:103], v[160:163], v[190:193], v[100:103]
	v_mfma_f32_16x16x32_bf16 v[100:103], v[164:167], v[194:197], v[100:103]
	v_mfma_f32_16x16x32_bf16 v[112:115], v[152:155], v[190:193], v[112:115]
	v_mfma_f32_16x16x32_bf16 v[112:115], v[156:159], v[194:197], v[112:115]
	v_mfma_f32_16x16x32_bf16 v[92:95], v[174:177], v[190:193], v[92:95]
	v_mfma_f32_16x16x32_bf16 v[92:95], v[178:181], v[194:197], v[92:95]
	v_mfma_f32_16x16x32_bf16 v[104:107], v[132:135], v[198:201], v[104:107]
	v_mfma_f32_16x16x32_bf16 v[104:107], v[136:139], v[208:211], v[104:107]
	v_mfma_f32_16x16x32_bf16 v[84:87], v[160:163], v[198:201], v[84:87]
	v_mfma_f32_16x16x32_bf16 v[84:87], v[164:167], v[208:211], v[84:87]
	v_mfma_f32_16x16x32_bf16 v[96:99], v[152:155], v[198:201], v[96:99]
	v_mfma_f32_16x16x32_bf16 v[96:99], v[156:159], v[208:211], v[96:99]
	v_mfma_f32_16x16x32_bf16 v[76:79], v[174:177], v[198:201], v[76:79]
	v_mfma_f32_16x16x32_bf16 v[76:79], v[178:181], v[208:211], v[76:79]
	v_mfma_f32_16x16x32_bf16 v[88:91], v[132:135], v[212:215], v[88:91]
	v_mfma_f32_16x16x32_bf16 v[88:91], v[136:139], v[216:219], v[88:91]
	v_mfma_f32_16x16x32_bf16 v[72:75], v[160:163], v[212:215], v[72:75]
	v_mfma_f32_16x16x32_bf16 v[72:75], v[164:167], v[216:219], v[72:75]
	v_mfma_f32_16x16x32_bf16 v[80:83], v[152:155], v[212:215], v[80:83]
	v_mfma_f32_16x16x32_bf16 v[80:83], v[156:159], v[216:219], v[80:83]
	v_mfma_f32_16x16x32_bf16 v[68:71], v[174:177], v[212:215], v[68:71]
	v_mfma_f32_16x16x32_bf16 v[68:71], v[178:181], v[216:219], v[68:71]
	s_setprio 0
	s_barrier
	s_sleep 2
	s_add_i32 s71, s71, s51
	v_lshl_add_u64 v[202:203], s[42:43], 0, v[2:3]
	s_mov_b32 m0, s71
	ds_read_b128 v[182:185], v171 offset:16384
	ds_read_b128 v[186:189], v171 offset:17408
	ds_read_b128 v[190:193], v171 offset:18432
	ds_read_b128 v[194:197], v171 offset:19456
	ds_read_b128 v[198:201], v171 offset:20480
	ds_read_b128 v[208:211], v171 offset:21504
	ds_read_b128 v[212:215], v171 offset:22528
	ds_read_b128 v[216:219], v171 offset:23552
	global_load_lds_dwordx4 v[202:203], off
	s_add_i32 m0, s71, 0x2000
	s_add_u32 s74, s42, 0x80000
	v_lshl_add_u64 v[204:205], s[42:43], 0, v[142:143]
	s_addc_u32 s75, s43, 0
	s_add_i32 s71, s73, s51
	global_load_lds_dwordx4 v[204:205], off
	v_lshl_add_u64 v[206:207], s[74:75], 0, v[2:3]
	s_mov_b32 m0, s71
	v_lshl_add_u64 v[220:221], s[44:45], 0, v[140:141]
	global_load_lds_dwordx4 v[206:207], off
	v_lshl_add_u64 v[206:207], s[74:75], 0, v[142:143]
	s_add_i32 m0, s71, 0x2000
	s_nop 0
	global_load_lds_dwordx4 v[206:207], off
	v_lshl_add_u64 v[206:207], s[44:45], 0, v[0:1]
	s_mov_b32 m0, s53
	s_nop 0
	global_load_lds_dwordx4 v[206:207], off
	s_mov_b32 m0, s54
	s_nop 0
	global_load_lds_dwordx4 v[220:221], off
	s_waitcnt vmcnt(8)
	s_waitcnt lgkmcnt(0)
	s_barrier
	s_setprio 1
	s_waitcnt lgkmcnt(0)
	v_mfma_f32_16x16x32_bf16 v[64:67], v[132:135], v[182:185], v[64:67]
	v_mfma_f32_16x16x32_bf16 v[64:67], v[136:139], v[186:189], v[64:67]
	v_mfma_f32_16x16x32_bf16 v[52:55], v[160:163], v[182:185], v[52:55]
	v_mfma_f32_16x16x32_bf16 v[52:55], v[164:167], v[186:189], v[52:55]
	v_mfma_f32_16x16x32_bf16 v[60:63], v[152:155], v[182:185], v[60:63]
	v_mfma_f32_16x16x32_bf16 v[60:63], v[156:159], v[186:189], v[60:63]
	v_mfma_f32_16x16x32_bf16 v[44:47], v[174:177], v[182:185], v[44:47]
	v_mfma_f32_16x16x32_bf16 v[44:47], v[178:181], v[186:189], v[44:47]
	v_mfma_f32_16x16x32_bf16 v[56:59], v[132:135], v[190:193], v[56:59]
	v_mfma_f32_16x16x32_bf16 v[56:59], v[136:139], v[194:197], v[56:59]
	v_mfma_f32_16x16x32_bf16 v[36:39], v[160:163], v[190:193], v[36:39]
	v_mfma_f32_16x16x32_bf16 v[36:39], v[164:167], v[194:197], v[36:39]
	v_mfma_f32_16x16x32_bf16 v[48:51], v[152:155], v[190:193], v[48:51]
	v_mfma_f32_16x16x32_bf16 v[48:51], v[156:159], v[194:197], v[48:51]
	v_mfma_f32_16x16x32_bf16 v[28:31], v[174:177], v[190:193], v[28:31]
	v_mfma_f32_16x16x32_bf16 v[28:31], v[178:181], v[194:197], v[28:31]
	v_mfma_f32_16x16x32_bf16 v[40:43], v[132:135], v[198:201], v[40:43]
	v_mfma_f32_16x16x32_bf16 v[40:43], v[136:139], v[208:211], v[40:43]
	v_mfma_f32_16x16x32_bf16 v[20:23], v[160:163], v[198:201], v[20:23]
	v_mfma_f32_16x16x32_bf16 v[20:23], v[164:167], v[208:211], v[20:23]
	v_mfma_f32_16x16x32_bf16 v[32:35], v[152:155], v[198:201], v[32:35]
	v_mfma_f32_16x16x32_bf16 v[32:35], v[156:159], v[208:211], v[32:35]
	v_mfma_f32_16x16x32_bf16 v[12:15], v[174:177], v[198:201], v[12:15]
	v_mfma_f32_16x16x32_bf16 v[12:15], v[178:181], v[208:211], v[12:15]
	v_mfma_f32_16x16x32_bf16 v[24:27], v[132:135], v[212:215], v[24:27]
	v_mfma_f32_16x16x32_bf16 v[24:27], v[136:139], v[216:219], v[24:27]
	v_mfma_f32_16x16x32_bf16 v[8:11], v[160:163], v[212:215], v[8:11]
	v_mfma_f32_16x16x32_bf16 v[8:11], v[164:167], v[216:219], v[8:11]
	v_mfma_f32_16x16x32_bf16 v[16:19], v[152:155], v[212:215], v[16:19]
	v_mfma_f32_16x16x32_bf16 v[16:19], v[156:159], v[216:219], v[16:19]
	v_mfma_f32_16x16x32_bf16 v[4:7], v[174:177], v[212:215], v[4:7]
	v_mfma_f32_16x16x32_bf16 v[4:7], v[178:181], v[216:219], v[4:7]
	s_setprio 0
	s_barrier
	s_sleep 2
	s_add_i32 s71, 0, 0x18000
	s_add_i32 s73, 0, 0x1c000
	v_add_u32_e32 v156, s71, v169
	v_add_u32_e32 v178, s73, v169
	ds_read_b128 v[132:135], v156
	ds_read_b128 v[136:139], v156 offset:1024
	ds_read_b128 v[152:155], v156 offset:2048
	ds_read_b128 v[156:159], v156 offset:3072
	ds_read_b128 v[160:163], v178
	ds_read_b128 v[164:167], v178 offset:1024
	ds_read_b128 v[174:177], v178 offset:2048
	ds_read_b128 v[178:181], v178 offset:3072
	s_add_u32 s44, s44, 0x80000
	s_addc_u32 s45, s45, 0
	s_mov_b32 m0, s55
	v_lshl_add_u64 v[222:223], s[44:45], 0, v[0:1]
	ds_read_b128 v[182:185], v171 offset:32768
	ds_read_b128 v[186:189], v171 offset:33792
	ds_read_b128 v[190:193], v171 offset:34816
	ds_read_b128 v[194:197], v171 offset:35840
	ds_read_b128 v[198:201], v171 offset:36864
	ds_read_b128 v[208:211], v171 offset:37888
	ds_read_b128 v[212:215], v171 offset:38912
	ds_read_b128 v[216:219], v171 offset:39936
	global_load_lds_dwordx4 v[222:223], off
	v_lshl_add_u64 v[222:223], s[44:45], 0, v[140:141]
	s_mov_b32 m0, s56
	s_nop 0
	global_load_lds_dwordx4 v[222:223], off
	s_waitcnt vmcnt(8)
	s_waitcnt lgkmcnt(0)
	s_barrier
	s_setprio 1
	s_waitcnt lgkmcnt(0)
	v_mfma_f32_16x16x32_bf16 v[128:131], v[132:135], v[182:185], v[128:131]
	v_mfma_f32_16x16x32_bf16 v[128:131], v[136:139], v[186:189], v[128:131]
	v_mfma_f32_16x16x32_bf16 v[116:119], v[160:163], v[182:185], v[116:119]
	v_mfma_f32_16x16x32_bf16 v[116:119], v[164:167], v[186:189], v[116:119]
	v_mfma_f32_16x16x32_bf16 v[124:127], v[152:155], v[182:185], v[124:127]
	v_mfma_f32_16x16x32_bf16 v[124:127], v[156:159], v[186:189], v[124:127]
	v_mfma_f32_16x16x32_bf16 v[108:111], v[174:177], v[182:185], v[108:111]
	v_mfma_f32_16x16x32_bf16 v[108:111], v[178:181], v[186:189], v[108:111]
	v_mfma_f32_16x16x32_bf16 v[120:123], v[132:135], v[190:193], v[120:123]
	v_mfma_f32_16x16x32_bf16 v[120:123], v[136:139], v[194:197], v[120:123]
	v_mfma_f32_16x16x32_bf16 v[100:103], v[160:163], v[190:193], v[100:103]
	v_mfma_f32_16x16x32_bf16 v[100:103], v[164:167], v[194:197], v[100:103]
	v_mfma_f32_16x16x32_bf16 v[112:115], v[152:155], v[190:193], v[112:115]
	v_mfma_f32_16x16x32_bf16 v[112:115], v[156:159], v[194:197], v[112:115]
	v_mfma_f32_16x16x32_bf16 v[92:95], v[174:177], v[190:193], v[92:95]
	v_mfma_f32_16x16x32_bf16 v[92:95], v[178:181], v[194:197], v[92:95]
	v_mfma_f32_16x16x32_bf16 v[104:107], v[132:135], v[198:201], v[104:107]
	v_mfma_f32_16x16x32_bf16 v[104:107], v[136:139], v[208:211], v[104:107]
	v_mfma_f32_16x16x32_bf16 v[84:87], v[160:163], v[198:201], v[84:87]
	v_mfma_f32_16x16x32_bf16 v[84:87], v[164:167], v[208:211], v[84:87]
	v_mfma_f32_16x16x32_bf16 v[96:99], v[152:155], v[198:201], v[96:99]
	v_mfma_f32_16x16x32_bf16 v[96:99], v[156:159], v[208:211], v[96:99]
	v_mfma_f32_16x16x32_bf16 v[76:79], v[174:177], v[198:201], v[76:79]
	v_mfma_f32_16x16x32_bf16 v[76:79], v[178:181], v[208:211], v[76:79]
	v_mfma_f32_16x16x32_bf16 v[88:91], v[132:135], v[212:215], v[88:91]
	v_mfma_f32_16x16x32_bf16 v[88:91], v[136:139], v[216:219], v[88:91]
	v_mfma_f32_16x16x32_bf16 v[72:75], v[160:163], v[212:215], v[72:75]
	v_mfma_f32_16x16x32_bf16 v[72:75], v[164:167], v[216:219], v[72:75]
	v_mfma_f32_16x16x32_bf16 v[80:83], v[152:155], v[212:215], v[80:83]
	v_mfma_f32_16x16x32_bf16 v[80:83], v[156:159], v[216:219], v[80:83]
	v_mfma_f32_16x16x32_bf16 v[68:71], v[174:177], v[212:215], v[68:71]
	v_mfma_f32_16x16x32_bf16 v[68:71], v[178:181], v[216:219], v[68:71]
	s_setprio 0
	s_barrier
	s_sleep 2
	s_add_i32 s44, s71, s51
	v_lshl_add_u64 v[202:203], v[202:203], 0, s[66:67]
	s_mov_b32 m0, s44
	ds_read_b128 v[182:185], v171 offset:49152
	ds_read_b128 v[186:189], v171 offset:50176
	ds_read_b128 v[190:193], v171 offset:51200
	ds_read_b128 v[194:197], v171 offset:52224
	ds_read_b128 v[198:201], v171 offset:53248
	ds_read_b128 v[208:211], v171 offset:54272
	ds_read_b128 v[212:215], v171 offset:55296
	ds_read_b128 v[216:219], v171 offset:56320
	global_load_lds_dwordx4 v[202:203], off
	s_add_i32 m0, s44, 0x2000
	s_add_u32 s42, s42, 0x80080
	v_lshl_add_u64 v[202:203], v[204:205], 0, s[66:67]
	s_addc_u32 s43, s43, 0
	s_add_i32 s44, s73, s51
	global_load_lds_dwordx4 v[202:203], off
	v_lshl_add_u64 v[202:203], s[42:43], 0, v[2:3]
	s_mov_b32 m0, s44
	s_nop 0
	global_load_lds_dwordx4 v[202:203], off
	v_lshl_add_u64 v[202:203], s[42:43], 0, v[142:143]
	s_add_i32 m0, s44, 0x2000
	s_nop 0
	global_load_lds_dwordx4 v[202:203], off
	v_lshl_add_u64 v[202:203], v[206:207], 0, s[66:67]
	s_mov_b32 m0, s65
	s_nop 0
	global_load_lds_dwordx4 v[202:203], off
	v_lshl_add_u64 v[202:203], v[220:221], 0, s[66:67]
	s_mov_b32 m0, s68
	s_nop 0
	global_load_lds_dwordx4 v[202:203], off
	s_waitcnt vmcnt(8)
	s_waitcnt lgkmcnt(0)
	s_barrier
	s_setprio 1
	s_waitcnt lgkmcnt(0)
	v_mfma_f32_16x16x32_bf16 v[64:67], v[132:135], v[182:185], v[64:67]
	v_mfma_f32_16x16x32_bf16 v[64:67], v[136:139], v[186:189], v[64:67]
	v_mfma_f32_16x16x32_bf16 v[52:55], v[160:163], v[182:185], v[52:55]
	v_mfma_f32_16x16x32_bf16 v[52:55], v[164:167], v[186:189], v[52:55]
	v_mfma_f32_16x16x32_bf16 v[60:63], v[152:155], v[182:185], v[60:63]
	v_mfma_f32_16x16x32_bf16 v[60:63], v[156:159], v[186:189], v[60:63]
	v_mfma_f32_16x16x32_bf16 v[44:47], v[174:177], v[182:185], v[44:47]
	v_mfma_f32_16x16x32_bf16 v[44:47], v[178:181], v[186:189], v[44:47]
	v_mfma_f32_16x16x32_bf16 v[56:59], v[132:135], v[190:193], v[56:59]
	v_mfma_f32_16x16x32_bf16 v[56:59], v[136:139], v[194:197], v[56:59]
	v_mfma_f32_16x16x32_bf16 v[36:39], v[160:163], v[190:193], v[36:39]
	v_mfma_f32_16x16x32_bf16 v[36:39], v[164:167], v[194:197], v[36:39]
	v_mfma_f32_16x16x32_bf16 v[48:51], v[152:155], v[190:193], v[48:51]
	v_mfma_f32_16x16x32_bf16 v[48:51], v[156:159], v[194:197], v[48:51]
	v_mfma_f32_16x16x32_bf16 v[28:31], v[174:177], v[190:193], v[28:31]
	v_mfma_f32_16x16x32_bf16 v[28:31], v[178:181], v[194:197], v[28:31]
	v_mfma_f32_16x16x32_bf16 v[40:43], v[132:135], v[198:201], v[40:43]
	v_mfma_f32_16x16x32_bf16 v[40:43], v[136:139], v[208:211], v[40:43]
	v_mfma_f32_16x16x32_bf16 v[20:23], v[160:163], v[198:201], v[20:23]
	v_mfma_f32_16x16x32_bf16 v[20:23], v[164:167], v[208:211], v[20:23]
	v_mfma_f32_16x16x32_bf16 v[32:35], v[152:155], v[198:201], v[32:35]
	v_mfma_f32_16x16x32_bf16 v[32:35], v[156:159], v[208:211], v[32:35]
	v_mfma_f32_16x16x32_bf16 v[12:15], v[174:177], v[198:201], v[12:15]
	v_mfma_f32_16x16x32_bf16 v[12:15], v[178:181], v[208:211], v[12:15]
	v_mfma_f32_16x16x32_bf16 v[24:27], v[132:135], v[212:215], v[24:27]
	v_mfma_f32_16x16x32_bf16 v[24:27], v[136:139], v[216:219], v[24:27]
	v_mfma_f32_16x16x32_bf16 v[8:11], v[160:163], v[212:215], v[8:11]
	v_mfma_f32_16x16x32_bf16 v[8:11], v[164:167], v[216:219], v[8:11]
	v_mfma_f32_16x16x32_bf16 v[16:19], v[152:155], v[212:215], v[16:19]
	v_mfma_f32_16x16x32_bf16 v[16:19], v[156:159], v[216:219], v[16:19]
	v_mfma_f32_16x16x32_bf16 v[4:7], v[174:177], v[212:215], v[4:7]
	v_mfma_f32_16x16x32_bf16 v[4:7], v[178:181], v[216:219], v[4:7]
	s_setprio 0
	s_barrier
	s_add_i32 s63, s63, 2
	s_add_u32 s40, s40, 0x100
	s_addc_u32 s41, s41, 0
	s_add_u32 s31, s31, 0x100
	s_addc_u32 s62, s62, 0
	s_cmp_gt_u32 s63, 29
	s_cbranch_scc0 .LBB0_147
	s_and_b64 vcc, exec, s[18:19]
	s_cbranch_vccz .LBB0_150
	s_barrier

.LBB0_211:
	s_sleep 2
	s_add_u32 s30, s28, 0xfff80080
	s_addc_u32 s31, s29, -1
	s_add_i32 s58, 0, 0x10000
	s_cmp_eq_u32 s57, 28
	s_cselect_b32 s39, s21, s31
	s_cselect_b32 s38, s53, s30
	v_add_u32_e32 v148, s58, v151
	s_cselect_b32 s31, s19, s56
	s_cselect_b32 s30, s54, s55
	s_add_i32 s60, 0, 0x14000
	ds_read_b128 v[140:143], v148
	ds_read_b128 v[144:147], v148 offset:1024
	ds_read_b128 v[156:159], v148 offset:2048
	ds_read_b128 v[160:163], v148 offset:3072
	v_add_u32_e32 v148, s60, v151
	ds_read_b128 v[164:167], v148
	ds_read_b128 v[168:171], v148 offset:1024
	ds_read_b128 v[172:175], v148 offset:2048
	ds_read_b128 v[176:179], v148 offset:3072
	s_add_i32 m0, s43, 0xc000
	ds_read_b128 v[180:183], v154
	ds_read_b128 v[184:187], v154 offset:1024
	ds_read_b128 v[188:191], v154 offset:2048
	ds_read_b128 v[192:195], v154 offset:3072
	ds_read_b128 v[196:199], v154 offset:4096
	ds_read_b128 v[200:203], v154 offset:5120
	ds_read_b128 v[208:211], v154 offset:6144
	ds_read_b128 v[212:215], v154 offset:7168
	global_load_lds_dwordx4 v136, s[28:29]
	s_add_i32 m0, s43, 0xe000
	s_nop 0
	global_load_lds_dwordx4 v138, s[28:29]
	s_waitcnt vmcnt(8)
	s_waitcnt lgkmcnt(0)
	s_barrier
	s_setprio 1
	s_waitcnt lgkmcnt(0)
	v_mfma_f32_16x16x32_bf16 v[128:131], v[140:143], v[180:183], v[128:131]
	v_mfma_f32_16x16x32_bf16 v[128:131], v[144:147], v[184:187], v[128:131]
	v_mfma_f32_16x16x32_bf16 v[120:123], v[164:167], v[180:183], v[120:123]
	v_mfma_f32_16x16x32_bf16 v[120:123], v[168:171], v[184:187], v[120:123]
	v_mfma_f32_16x16x32_bf16 v[124:127], v[156:159], v[180:183], v[124:127]
	v_mfma_f32_16x16x32_bf16 v[124:127], v[160:163], v[184:187], v[124:127]
	v_mfma_f32_16x16x32_bf16 v[116:119], v[172:175], v[180:183], v[116:119]
	v_mfma_f32_16x16x32_bf16 v[116:119], v[176:179], v[184:187], v[116:119]
	v_mfma_f32_16x16x32_bf16 v[112:115], v[140:143], v[188:191], v[112:115]
	v_mfma_f32_16x16x32_bf16 v[112:115], v[144:147], v[192:195], v[112:115]
	v_mfma_f32_16x16x32_bf16 v[104:107], v[164:167], v[188:191], v[104:107]
	v_mfma_f32_16x16x32_bf16 v[104:107], v[168:171], v[192:195], v[104:107]
	v_mfma_f32_16x16x32_bf16 v[108:111], v[156:159], v[188:191], v[108:111]
	v_mfma_f32_16x16x32_bf16 v[108:111], v[160:163], v[192:195], v[108:111]
	v_mfma_f32_16x16x32_bf16 v[100:103], v[172:175], v[188:191], v[100:103]
	v_mfma_f32_16x16x32_bf16 v[100:103], v[176:179], v[192:195], v[100:103]
	v_mfma_f32_16x16x32_bf16 v[96:99], v[140:143], v[196:199], v[96:99]
	v_mfma_f32_16x16x32_bf16 v[96:99], v[144:147], v[200:203], v[96:99]
	v_mfma_f32_16x16x32_bf16 v[88:91], v[164:167], v[196:199], v[88:91]
	v_mfma_f32_16x16x32_bf16 v[88:91], v[168:171], v[200:203], v[88:91]
	v_mfma_f32_16x16x32_bf16 v[92:95], v[156:159], v[196:199], v[92:95]
	v_mfma_f32_16x16x32_bf16 v[92:95], v[160:163], v[200:203], v[92:95]
	v_mfma_f32_16x16x32_bf16 v[84:87], v[172:175], v[196:199], v[84:87]
	v_mfma_f32_16x16x32_bf16 v[84:87], v[176:179], v[200:203], v[84:87]
	v_mfma_f32_16x16x32_bf16 v[80:83], v[140:143], v[208:211], v[80:83]
	v_mfma_f32_16x16x32_bf16 v[80:83], v[144:147], v[212:215], v[80:83]
	v_mfma_f32_16x16x32_bf16 v[72:75], v[164:167], v[208:211], v[72:75]
	v_mfma_f32_16x16x32_bf16 v[72:75], v[168:171], v[212:215], v[72:75]
	v_mfma_f32_16x16x32_bf16 v[76:79], v[156:159], v[208:211], v[76:79]
	v_mfma_f32_16x16x32_bf16 v[76:79], v[160:163], v[212:215], v[76:79]
	v_mfma_f32_16x16x32_bf16 v[68:71], v[172:175], v[208:211], v[68:71]
	v_mfma_f32_16x16x32_bf16 v[68:71], v[176:179], v[212:215], v[68:71]
	s_setprio 0
	s_barrier
	s_sleep 2
	s_add_i32 s58, s58, s41
	s_mov_b32 m0, s58
	ds_read_b128 v[180:183], v154 offset:16384
	ds_read_b128 v[184:187], v154 offset:17408
	ds_read_b128 v[188:191], v154 offset:18432
	ds_read_b128 v[192:195], v154 offset:19456
	ds_read_b128 v[196:199], v154 offset:20480
	ds_read_b128 v[200:203], v154 offset:21504
	ds_read_b128 v[208:211], v154 offset:22528
	ds_read_b128 v[212:215], v154 offset:23552
	global_load_lds_dwordx4 v2, s[30:31]
	s_add_i32 m0, s58, 0x2000
	s_add_u32 s62, s30, 0x80000
	s_addc_u32 s63, s31, 0
	s_add_i32 s58, s60, s41
	global_load_lds_dwordx4 v0, s[30:31]
	s_mov_b32 m0, s58
	s_nop 0
	global_load_lds_dwordx4 v2, s[62:63]
	s_add_i32 m0, s58, 0x2000
	s_nop 0
	global_load_lds_dwordx4 v0, s[62:63]
	s_mov_b32 m0, s43
	s_nop 0
	global_load_lds_dwordx4 v134, s[38:39]
	s_mov_b32 m0, s44
	s_nop 0
	global_load_lds_dwordx4 v132, s[38:39]
	s_waitcnt vmcnt(8)
	s_waitcnt lgkmcnt(0)
	s_barrier
	s_setprio 1
	s_waitcnt lgkmcnt(0)
	v_mfma_f32_16x16x32_bf16 v[64:67], v[140:143], v[180:183], v[64:67]
	v_mfma_f32_16x16x32_bf16 v[64:67], v[144:147], v[184:187], v[64:67]
	v_mfma_f32_16x16x32_bf16 v[56:59], v[164:167], v[180:183], v[56:59]
	v_mfma_f32_16x16x32_bf16 v[56:59], v[168:171], v[184:187], v[56:59]
	v_mfma_f32_16x16x32_bf16 v[60:63], v[156:159], v[180:183], v[60:63]
	v_mfma_f32_16x16x32_bf16 v[60:63], v[160:163], v[184:187], v[60:63]
	v_mfma_f32_16x16x32_bf16 v[52:55], v[172:175], v[180:183], v[52:55]
	v_mfma_f32_16x16x32_bf16 v[52:55], v[176:179], v[184:187], v[52:55]
	v_mfma_f32_16x16x32_bf16 v[48:51], v[140:143], v[188:191], v[48:51]
	v_mfma_f32_16x16x32_bf16 v[48:51], v[144:147], v[192:195], v[48:51]
	v_mfma_f32_16x16x32_bf16 v[40:43], v[164:167], v[188:191], v[40:43]
	v_mfma_f32_16x16x32_bf16 v[40:43], v[168:171], v[192:195], v[40:43]
	v_mfma_f32_16x16x32_bf16 v[44:47], v[156:159], v[188:191], v[44:47]
	v_mfma_f32_16x16x32_bf16 v[44:47], v[160:163], v[192:195], v[44:47]
	v_mfma_f32_16x16x32_bf16 v[36:39], v[172:175], v[188:191], v[36:39]
	v_mfma_f32_16x16x32_bf16 v[36:39], v[176:179], v[192:195], v[36:39]
	v_mfma_f32_16x16x32_bf16 v[32:35], v[140:143], v[196:199], v[32:35]
	v_mfma_f32_16x16x32_bf16 v[32:35], v[144:147], v[200:203], v[32:35]
	v_mfma_f32_16x16x32_bf16 v[24:27], v[164:167], v[196:199], v[24:27]
	v_mfma_f32_16x16x32_bf16 v[24:27], v[168:171], v[200:203], v[24:27]
	v_mfma_f32_16x16x32_bf16 v[28:31], v[156:159], v[196:199], v[28:31]
	v_mfma_f32_16x16x32_bf16 v[28:31], v[160:163], v[200:203], v[28:31]
	v_mfma_f32_16x16x32_bf16 v[20:23], v[172:175], v[196:199], v[20:23]
	v_mfma_f32_16x16x32_bf16 v[20:23], v[176:179], v[200:203], v[20:23]
	v_mfma_f32_16x16x32_bf16 v[16:19], v[140:143], v[208:211], v[16:19]
	v_mfma_f32_16x16x32_bf16 v[16:19], v[144:147], v[212:215], v[16:19]
	v_mfma_f32_16x16x32_bf16 v[8:11], v[164:167], v[208:211], v[8:11]
	v_mfma_f32_16x16x32_bf16 v[8:11], v[168:171], v[212:215], v[8:11]
	v_mfma_f32_16x16x32_bf16 v[12:15], v[156:159], v[208:211], v[12:15]
	v_mfma_f32_16x16x32_bf16 v[12:15], v[160:163], v[212:215], v[12:15]
	v_mfma_f32_16x16x32_bf16 v[4:7], v[172:175], v[208:211], v[4:7]
	v_mfma_f32_16x16x32_bf16 v[4:7], v[176:179], v[212:215], v[4:7]
	s_setprio 0
	s_barrier
	s_sleep 2
	s_add_i32 s58, 0, 0x18000
	v_add_u32_e32 v155, s58, v151
	s_add_i32 s60, 0, 0x1c000
	ds_read_b128 v[140:143], v155
	ds_read_b128 v[144:147], v155 offset:1024
	ds_read_b128 v[156:159], v155 offset:2048
	ds_read_b128 v[160:163], v155 offset:3072
	v_add_u32_e32 v155, s60, v151
	ds_read_b128 v[164:167], v155
	ds_read_b128 v[168:171], v155 offset:1024
	ds_read_b128 v[172:175], v155 offset:2048
	ds_read_b128 v[176:179], v155 offset:3072
	s_add_u32 s38, s38, 0x80000
	s_addc_u32 s39, s39, 0
	s_mov_b32 m0, s45
	ds_read_b128 v[180:183], v154 offset:32768
	ds_read_b128 v[184:187], v154 offset:33792
	ds_read_b128 v[188:191], v154 offset:34816
	ds_read_b128 v[192:195], v154 offset:35840
	ds_read_b128 v[196:199], v154 offset:36864
	ds_read_b128 v[200:203], v154 offset:37888
	ds_read_b128 v[208:211], v154 offset:38912
	ds_read_b128 v[212:215], v154 offset:39936
	global_load_lds_dwordx4 v134, s[38:39]
	s_mov_b32 m0, s47
	s_nop 0
	global_load_lds_dwordx4 v132, s[38:39]
	s_waitcnt vmcnt(8)
	s_waitcnt lgkmcnt(0)
	s_barrier
	s_setprio 1
	s_waitcnt lgkmcnt(0)
	v_mfma_f32_16x16x32_bf16 v[128:131], v[140:143], v[180:183], v[128:131]
	v_mfma_f32_16x16x32_bf16 v[128:131], v[144:147], v[184:187], v[128:131]
	v_mfma_f32_16x16x32_bf16 v[120:123], v[164:167], v[180:183], v[120:123]
	v_mfma_f32_16x16x32_bf16 v[120:123], v[168:171], v[184:187], v[120:123]
	v_mfma_f32_16x16x32_bf16 v[124:127], v[156:159], v[180:183], v[124:127]
	v_mfma_f32_16x16x32_bf16 v[124:127], v[160:163], v[184:187], v[124:127]
	v_mfma_f32_16x16x32_bf16 v[116:119], v[172:175], v[180:183], v[116:119]
	v_mfma_f32_16x16x32_bf16 v[116:119], v[176:179], v[184:187], v[116:119]
	v_mfma_f32_16x16x32_bf16 v[112:115], v[140:143], v[188:191], v[112:115]
	v_mfma_f32_16x16x32_bf16 v[112:115], v[144:147], v[192:195], v[112:115]
	v_mfma_f32_16x16x32_bf16 v[104:107], v[164:167], v[188:191], v[104:107]
	v_mfma_f32_16x16x32_bf16 v[104:107], v[168:171], v[192:195], v[104:107]
	v_mfma_f32_16x16x32_bf16 v[108:111], v[156:159], v[188:191], v[108:111]
	v_mfma_f32_16x16x32_bf16 v[108:111], v[160:163], v[192:195], v[108:111]
	v_mfma_f32_16x16x32_bf16 v[100:103], v[172:175], v[188:191], v[100:103]
	v_mfma_f32_16x16x32_bf16 v[100:103], v[176:179], v[192:195], v[100:103]
	v_mfma_f32_16x16x32_bf16 v[96:99], v[140:143], v[196:199], v[96:99]
	v_mfma_f32_16x16x32_bf16 v[96:99], v[144:147], v[200:203], v[96:99]
	v_mfma_f32_16x16x32_bf16 v[88:91], v[164:167], v[196:199], v[88:91]
	v_mfma_f32_16x16x32_bf16 v[88:91], v[168:171], v[200:203], v[88:91]
	v_mfma_f32_16x16x32_bf16 v[92:95], v[156:159], v[196:199], v[92:95]
	v_mfma_f32_16x16x32_bf16 v[92:95], v[160:163], v[200:203], v[92:95]
	v_mfma_f32_16x16x32_bf16 v[84:87], v[172:175], v[196:199], v[84:87]
	v_mfma_f32_16x16x32_bf16 v[84:87], v[176:179], v[200:203], v[84:87]
	v_mfma_f32_16x16x32_bf16 v[80:83], v[140:143], v[208:211], v[80:83]
	v_mfma_f32_16x16x32_bf16 v[80:83], v[144:147], v[212:215], v[80:83]
	v_mfma_f32_16x16x32_bf16 v[72:75], v[164:167], v[208:211], v[72:75]
	v_mfma_f32_16x16x32_bf16 v[72:75], v[168:171], v[212:215], v[72:75]
	v_mfma_f32_16x16x32_bf16 v[76:79], v[156:159], v[208:211], v[76:79]
	v_mfma_f32_16x16x32_bf16 v[76:79], v[160:163], v[212:215], v[76:79]
	v_mfma_f32_16x16x32_bf16 v[68:71], v[172:175], v[208:211], v[68:71]
	v_mfma_f32_16x16x32_bf16 v[68:71], v[176:179], v[212:215], v[68:71]
	s_setprio 0
	s_barrier
	s_sleep 2
	s_add_i32 s62, s58, s41
	s_add_u32 s30, s30, 0x80
	s_addc_u32 s31, s31, 0
	s_mov_b32 m0, s62
	ds_read_b128 v[180:183], v154 offset:49152
	ds_read_b128 v[184:187], v154 offset:50176
	ds_read_b128 v[188:191], v154 offset:51200
	ds_read_b128 v[192:195], v154 offset:52224
	ds_read_b128 v[196:199], v154 offset:53248
	ds_read_b128 v[200:203], v154 offset:54272
	ds_read_b128 v[208:211], v154 offset:55296
	ds_read_b128 v[212:215], v154 offset:56320
	global_load_lds_dwordx4 v2, s[30:31]
	s_add_i32 m0, s62, 0x2000
	s_nop 0
	s_add_i32 s62, s60, s41
	global_load_lds_dwordx4 v0, s[30:31]
	s_add_u32 s30, s30, 0x80000
	s_addc_u32 s31, s31, 0
	s_mov_b32 m0, s62
	s_nop 0
	global_load_lds_dwordx4 v2, s[30:31]
	s_add_i32 m0, s62, 0x2000
	s_nop 0
	global_load_lds_dwordx4 v0, s[30:31]
	s_sub_u32 s38, s38, 0x7ff80
	s_subb_u32 s39, s39, 0
	s_mov_b32 m0, s48
	s_nop 0
	global_load_lds_dwordx4 v134, s[38:39]
	s_mov_b32 m0, s49
	s_nop 0
	global_load_lds_dwordx4 v132, s[38:39]
	s_waitcnt vmcnt(8)
	s_waitcnt lgkmcnt(0)
	s_barrier
	s_setprio 1
	s_waitcnt lgkmcnt(0)
	v_mfma_f32_16x16x32_bf16 v[64:67], v[140:143], v[180:183], v[64:67]
	v_mfma_f32_16x16x32_bf16 v[64:67], v[144:147], v[184:187], v[64:67]
	v_mfma_f32_16x16x32_bf16 v[56:59], v[164:167], v[180:183], v[56:59]
	v_mfma_f32_16x16x32_bf16 v[56:59], v[168:171], v[184:187], v[56:59]
	v_mfma_f32_16x16x32_bf16 v[60:63], v[156:159], v[180:183], v[60:63]
	v_mfma_f32_16x16x32_bf16 v[60:63], v[160:163], v[184:187], v[60:63]
	v_mfma_f32_16x16x32_bf16 v[52:55], v[172:175], v[180:183], v[52:55]
	v_mfma_f32_16x16x32_bf16 v[52:55], v[176:179], v[184:187], v[52:55]
	v_mfma_f32_16x16x32_bf16 v[48:51], v[140:143], v[188:191], v[48:51]
	v_mfma_f32_16x16x32_bf16 v[48:51], v[144:147], v[192:195], v[48:51]
	v_mfma_f32_16x16x32_bf16 v[40:43], v[164:167], v[188:191], v[40:43]
	v_mfma_f32_16x16x32_bf16 v[40:43], v[168:171], v[192:195], v[40:43]
	v_mfma_f32_16x16x32_bf16 v[44:47], v[156:159], v[188:191], v[44:47]
	v_mfma_f32_16x16x32_bf16 v[44:47], v[160:163], v[192:195], v[44:47]
	v_mfma_f32_16x16x32_bf16 v[36:39], v[172:175], v[188:191], v[36:39]
	v_mfma_f32_16x16x32_bf16 v[36:39], v[176:179], v[192:195], v[36:39]
	v_mfma_f32_16x16x32_bf16 v[32:35], v[140:143], v[196:199], v[32:35]
	v_mfma_f32_16x16x32_bf16 v[32:35], v[144:147], v[200:203], v[32:35]
	v_mfma_f32_16x16x32_bf16 v[24:27], v[164:167], v[196:199], v[24:27]
	v_mfma_f32_16x16x32_bf16 v[24:27], v[168:171], v[200:203], v[24:27]
	v_mfma_f32_16x16x32_bf16 v[28:31], v[156:159], v[196:199], v[28:31]
	v_mfma_f32_16x16x32_bf16 v[28:31], v[160:163], v[200:203], v[28:31]
	v_mfma_f32_16x16x32_bf16 v[20:23], v[172:175], v[196:199], v[20:23]
	v_mfma_f32_16x16x32_bf16 v[20:23], v[176:179], v[200:203], v[20:23]
	v_mfma_f32_16x16x32_bf16 v[16:19], v[140:143], v[208:211], v[16:19]
	v_mfma_f32_16x16x32_bf16 v[16:19], v[144:147], v[212:215], v[16:19]
	v_mfma_f32_16x16x32_bf16 v[8:11], v[164:167], v[208:211], v[8:11]
	v_mfma_f32_16x16x32_bf16 v[8:11], v[168:171], v[212:215], v[8:11]
	v_mfma_f32_16x16x32_bf16 v[12:15], v[156:159], v[208:211], v[12:15]
	v_mfma_f32_16x16x32_bf16 v[12:15], v[160:163], v[212:215], v[12:15]
	v_mfma_f32_16x16x32_bf16 v[4:7], v[172:175], v[208:211], v[4:7]
	v_mfma_f32_16x16x32_bf16 v[4:7], v[176:179], v[212:215], v[4:7]
	s_setprio 0
	s_barrier
	s_add_i32 s57, s57, 2
	s_add_u32 s28, s28, 0x100
	s_addc_u32 s29, s29, 0
	s_add_u32 s55, s55, 0x100
	s_addc_u32 s56, s56, 0
	s_cmp_gt_u32 s57, 29
	s_cbranch_scc0 .LBB0_211
	s_and_b64 vcc, exec, s[16:17]
	s_cbranch_vccz .LBB0_214
	s_barrier

.LBB0_301:
	s_sleep 2
	s_add_u32 s18, s16, 0x100
	s_addc_u32 s19, s17, 0
	s_add_i32 s49, 0, 0x10000
	s_cmpk_eq_i32 s48, 0x54
	s_cselect_b32 s23, s13, s19
	s_cselect_b32 s22, s12, s18
	s_cselect_b32 s21, s15, s41
	s_cselect_b32 s20, s14, s40
	s_add_i32 s50, 0, 0x14000
	v_add_u32_e32 v144, s49, v219
	v_add_u32_e32 v160, s50, v219
	ds_read_b128 v[124:127], v144
	ds_read_b128 v[128:131], v144 offset:1024
	ds_read_b128 v[140:143], v144 offset:2048
	ds_read_b128 v[144:147], v144 offset:3072
	ds_read_b128 v[148:151], v160
	ds_read_b128 v[152:155], v160 offset:1024
	ds_read_b128 v[156:159], v160 offset:2048
	ds_read_b128 v[160:163], v160 offset:3072
	v_lshl_add_u64 v[204:205], s[16:17], 0, v[192:193]
	s_add_i32 m0, s28, 0xc000
	ds_read_b128 v[164:167], v221
	ds_read_b128 v[168:171], v221 offset:1024
	ds_read_b128 v[172:175], v221 offset:2048
	ds_read_b128 v[176:179], v221 offset:3072
	ds_read_b128 v[180:183], v221 offset:4096
	ds_read_b128 v[184:187], v221 offset:5120
	ds_read_b128 v[196:199], v221 offset:6144
	ds_read_b128 v[200:203], v221 offset:7168
	global_load_lds_dwordx4 v[204:205], off
	v_lshl_add_u64 v[204:205], s[16:17], 0, v[194:195]
	s_add_i32 m0, s28, 0xe000
	s_nop 0
	global_load_lds_dwordx4 v[204:205], off
	s_waitcnt vmcnt(8)
	s_waitcnt lgkmcnt(0)
	s_barrier
	s_setprio 1
	s_waitcnt lgkmcnt(0)
	v_mfma_f32_16x16x32_bf16 v[136:139], v[124:127], v[164:167], v[136:139]
	v_mfma_f32_16x16x32_bf16 v[136:139], v[128:131], v[168:171], v[136:139]
	v_mfma_f32_16x16x32_bf16 v[120:123], v[148:151], v[164:167], v[120:123]
	v_mfma_f32_16x16x32_bf16 v[120:123], v[152:155], v[168:171], v[120:123]
	v_mfma_f32_16x16x32_bf16 v[132:135], v[140:143], v[164:167], v[132:135]
	v_mfma_f32_16x16x32_bf16 v[132:135], v[144:147], v[168:171], v[132:135]
	v_mfma_f32_16x16x32_bf16 v[116:119], v[156:159], v[164:167], v[116:119]
	v_mfma_f32_16x16x32_bf16 v[116:119], v[160:163], v[168:171], v[116:119]
	v_mfma_f32_16x16x32_bf16 v[112:115], v[124:127], v[172:175], v[112:115]
	v_mfma_f32_16x16x32_bf16 v[112:115], v[128:131], v[176:179], v[112:115]
	v_mfma_f32_16x16x32_bf16 v[104:107], v[148:151], v[172:175], v[104:107]
	v_mfma_f32_16x16x32_bf16 v[104:107], v[152:155], v[176:179], v[104:107]
	v_mfma_f32_16x16x32_bf16 v[108:111], v[140:143], v[172:175], v[108:111]
	v_mfma_f32_16x16x32_bf16 v[108:111], v[144:147], v[176:179], v[108:111]
	v_mfma_f32_16x16x32_bf16 v[100:103], v[156:159], v[172:175], v[100:103]
	v_mfma_f32_16x16x32_bf16 v[100:103], v[160:163], v[176:179], v[100:103]
	v_mfma_f32_16x16x32_bf16 v[96:99], v[124:127], v[180:183], v[96:99]
	v_mfma_f32_16x16x32_bf16 v[96:99], v[128:131], v[184:187], v[96:99]
	v_mfma_f32_16x16x32_bf16 v[88:91], v[148:151], v[180:183], v[88:91]
	v_mfma_f32_16x16x32_bf16 v[88:91], v[152:155], v[184:187], v[88:91]
	v_mfma_f32_16x16x32_bf16 v[92:95], v[140:143], v[180:183], v[92:95]
	v_mfma_f32_16x16x32_bf16 v[92:95], v[144:147], v[184:187], v[92:95]
	v_mfma_f32_16x16x32_bf16 v[84:87], v[156:159], v[180:183], v[84:87]
	v_mfma_f32_16x16x32_bf16 v[84:87], v[160:163], v[184:187], v[84:87]
	v_mfma_f32_16x16x32_bf16 v[80:83], v[124:127], v[196:199], v[80:83]
	v_mfma_f32_16x16x32_bf16 v[80:83], v[128:131], v[200:203], v[80:83]
	v_mfma_f32_16x16x32_bf16 v[72:75], v[148:151], v[196:199], v[72:75]
	v_mfma_f32_16x16x32_bf16 v[72:75], v[152:155], v[200:203], v[72:75]
	v_mfma_f32_16x16x32_bf16 v[76:79], v[140:143], v[196:199], v[76:79]
	v_mfma_f32_16x16x32_bf16 v[76:79], v[144:147], v[200:203], v[76:79]
	v_mfma_f32_16x16x32_bf16 v[68:71], v[156:159], v[196:199], v[68:71]
	v_mfma_f32_16x16x32_bf16 v[68:71], v[160:163], v[200:203], v[68:71]
	s_setprio 0
	s_barrier
	s_sleep 2
	s_add_i32 s16, s49, s2
	v_lshl_add_u64 v[204:205], s[20:21], 0, v[2:3]
	s_mov_b32 m0, s16
	ds_read_b128 v[164:167], v221 offset:16384
	ds_read_b128 v[168:171], v221 offset:17408
	ds_read_b128 v[172:175], v221 offset:18432
	ds_read_b128 v[176:179], v221 offset:19456
	ds_read_b128 v[180:183], v221 offset:20480
	ds_read_b128 v[184:187], v221 offset:21504
	ds_read_b128 v[196:199], v221 offset:22528
	ds_read_b128 v[200:203], v221 offset:23552
	global_load_lds_dwordx4 v[204:205], off
	s_add_i32 m0, s16, 0x2000
	s_add_u32 s16, s20, 0x160000
	v_lshl_add_u64 v[206:207], s[20:21], 0, v[190:191]
	s_addc_u32 s17, s21, 0
	s_add_i32 s49, s50, s2
	global_load_lds_dwordx4 v[206:207], off
	v_lshl_add_u64 v[208:209], s[16:17], 0, v[2:3]
	s_mov_b32 m0, s49
	v_lshl_add_u64 v[210:211], s[22:23], 0, v[188:189]
	global_load_lds_dwordx4 v[208:209], off
	v_lshl_add_u64 v[208:209], s[16:17], 0, v[190:191]
	s_add_i32 m0, s49, 0x2000
	s_nop 0
	global_load_lds_dwordx4 v[208:209], off
	v_lshl_add_u64 v[208:209], s[22:23], 0, v[0:1]
	s_mov_b32 m0, s28
	s_nop 0
	global_load_lds_dwordx4 v[208:209], off
	s_mov_b32 m0, s29
	s_nop 0
	global_load_lds_dwordx4 v[210:211], off
	s_waitcnt vmcnt(8)
	s_waitcnt lgkmcnt(0)
	s_barrier
	s_setprio 1
	s_waitcnt lgkmcnt(0)
	v_mfma_f32_16x16x32_bf16 v[64:67], v[124:127], v[164:167], v[64:67]
	v_mfma_f32_16x16x32_bf16 v[64:67], v[128:131], v[168:171], v[64:67]
	v_mfma_f32_16x16x32_bf16 v[56:59], v[148:151], v[164:167], v[56:59]
	v_mfma_f32_16x16x32_bf16 v[56:59], v[152:155], v[168:171], v[56:59]
	v_mfma_f32_16x16x32_bf16 v[60:63], v[140:143], v[164:167], v[60:63]
	v_mfma_f32_16x16x32_bf16 v[60:63], v[144:147], v[168:171], v[60:63]
	v_mfma_f32_16x16x32_bf16 v[52:55], v[156:159], v[164:167], v[52:55]
	v_mfma_f32_16x16x32_bf16 v[52:55], v[160:163], v[168:171], v[52:55]
	v_mfma_f32_16x16x32_bf16 v[48:51], v[124:127], v[172:175], v[48:51]
	v_mfma_f32_16x16x32_bf16 v[48:51], v[128:131], v[176:179], v[48:51]
	v_mfma_f32_16x16x32_bf16 v[40:43], v[148:151], v[172:175], v[40:43]
	v_mfma_f32_16x16x32_bf16 v[40:43], v[152:155], v[176:179], v[40:43]
	v_mfma_f32_16x16x32_bf16 v[44:47], v[140:143], v[172:175], v[44:47]
	v_mfma_f32_16x16x32_bf16 v[44:47], v[144:147], v[176:179], v[44:47]
	v_mfma_f32_16x16x32_bf16 v[36:39], v[156:159], v[172:175], v[36:39]
	v_mfma_f32_16x16x32_bf16 v[36:39], v[160:163], v[176:179], v[36:39]
	v_mfma_f32_16x16x32_bf16 v[32:35], v[124:127], v[180:183], v[32:35]
	v_mfma_f32_16x16x32_bf16 v[32:35], v[128:131], v[184:187], v[32:35]
	v_mfma_f32_16x16x32_bf16 v[24:27], v[148:151], v[180:183], v[24:27]
	v_mfma_f32_16x16x32_bf16 v[24:27], v[152:155], v[184:187], v[24:27]
	v_mfma_f32_16x16x32_bf16 v[28:31], v[140:143], v[180:183], v[28:31]
	v_mfma_f32_16x16x32_bf16 v[28:31], v[144:147], v[184:187], v[28:31]
	v_mfma_f32_16x16x32_bf16 v[20:23], v[156:159], v[180:183], v[20:23]
	v_mfma_f32_16x16x32_bf16 v[20:23], v[160:163], v[184:187], v[20:23]
	v_mfma_f32_16x16x32_bf16 v[16:19], v[124:127], v[196:199], v[16:19]
	v_mfma_f32_16x16x32_bf16 v[16:19], v[128:131], v[200:203], v[16:19]
	v_mfma_f32_16x16x32_bf16 v[8:11], v[148:151], v[196:199], v[8:11]
	v_mfma_f32_16x16x32_bf16 v[8:11], v[152:155], v[200:203], v[8:11]
	v_mfma_f32_16x16x32_bf16 v[12:15], v[140:143], v[196:199], v[12:15]
	v_mfma_f32_16x16x32_bf16 v[12:15], v[144:147], v[200:203], v[12:15]
	v_mfma_f32_16x16x32_bf16 v[4:7], v[156:159], v[196:199], v[4:7]
	v_mfma_f32_16x16x32_bf16 v[4:7], v[160:163], v[200:203], v[4:7]
	s_setprio 0
	s_barrier
	s_sleep 2
	s_add_i32 s49, 0, 0x18000
	s_add_i32 s50, 0, 0x1c000
	v_add_u32_e32 v144, s49, v219
	v_add_u32_e32 v160, s50, v219
	ds_read_b128 v[124:127], v144
	ds_read_b128 v[128:131], v144 offset:1024
	ds_read_b128 v[140:143], v144 offset:2048
	ds_read_b128 v[144:147], v144 offset:3072
	ds_read_b128 v[148:151], v160
	ds_read_b128 v[152:155], v160 offset:1024
	ds_read_b128 v[156:159], v160 offset:2048
	ds_read_b128 v[160:163], v160 offset:3072
	s_add_u32 s16, s22, 0x160000
	s_addc_u32 s17, s23, 0
	s_mov_b32 m0, s30
	v_lshl_add_u64 v[212:213], s[16:17], 0, v[0:1]
	ds_read_b128 v[164:167], v221 offset:32768
	ds_read_b128 v[168:171], v221 offset:33792
	ds_read_b128 v[172:175], v221 offset:34816
	ds_read_b128 v[176:179], v221 offset:35840
	ds_read_b128 v[180:183], v221 offset:36864
	ds_read_b128 v[184:187], v221 offset:37888
	ds_read_b128 v[196:199], v221 offset:38912
	ds_read_b128 v[200:203], v221 offset:39936
	global_load_lds_dwordx4 v[212:213], off
	v_lshl_add_u64 v[212:213], s[16:17], 0, v[188:189]
	s_mov_b32 m0, s31
	s_nop 0
	global_load_lds_dwordx4 v[212:213], off
	s_waitcnt vmcnt(8)
	s_waitcnt lgkmcnt(0)
	s_barrier
	s_setprio 1
	s_waitcnt lgkmcnt(0)
	v_mfma_f32_16x16x32_bf16 v[136:139], v[124:127], v[164:167], v[136:139]
	v_mfma_f32_16x16x32_bf16 v[136:139], v[128:131], v[168:171], v[136:139]
	v_mfma_f32_16x16x32_bf16 v[120:123], v[148:151], v[164:167], v[120:123]
	v_mfma_f32_16x16x32_bf16 v[120:123], v[152:155], v[168:171], v[120:123]
	v_mfma_f32_16x16x32_bf16 v[132:135], v[140:143], v[164:167], v[132:135]
	v_mfma_f32_16x16x32_bf16 v[132:135], v[144:147], v[168:171], v[132:135]
	v_mfma_f32_16x16x32_bf16 v[116:119], v[156:159], v[164:167], v[116:119]
	v_mfma_f32_16x16x32_bf16 v[116:119], v[160:163], v[168:171], v[116:119]
	v_mfma_f32_16x16x32_bf16 v[112:115], v[124:127], v[172:175], v[112:115]
	v_mfma_f32_16x16x32_bf16 v[112:115], v[128:131], v[176:179], v[112:115]
	v_mfma_f32_16x16x32_bf16 v[104:107], v[148:151], v[172:175], v[104:107]
	v_mfma_f32_16x16x32_bf16 v[104:107], v[152:155], v[176:179], v[104:107]
	v_mfma_f32_16x16x32_bf16 v[108:111], v[140:143], v[172:175], v[108:111]
	v_mfma_f32_16x16x32_bf16 v[108:111], v[144:147], v[176:179], v[108:111]
	v_mfma_f32_16x16x32_bf16 v[100:103], v[156:159], v[172:175], v[100:103]
	v_mfma_f32_16x16x32_bf16 v[100:103], v[160:163], v[176:179], v[100:103]
	v_mfma_f32_16x16x32_bf16 v[96:99], v[124:127], v[180:183], v[96:99]
	v_mfma_f32_16x16x32_bf16 v[96:99], v[128:131], v[184:187], v[96:99]
	v_mfma_f32_16x16x32_bf16 v[88:91], v[148:151], v[180:183], v[88:91]
	v_mfma_f32_16x16x32_bf16 v[88:91], v[152:155], v[184:187], v[88:91]
	v_mfma_f32_16x16x32_bf16 v[92:95], v[140:143], v[180:183], v[92:95]
	v_mfma_f32_16x16x32_bf16 v[92:95], v[144:147], v[184:187], v[92:95]
	v_mfma_f32_16x16x32_bf16 v[84:87], v[156:159], v[180:183], v[84:87]
	v_mfma_f32_16x16x32_bf16 v[84:87], v[160:163], v[184:187], v[84:87]
	v_mfma_f32_16x16x32_bf16 v[80:83], v[124:127], v[196:199], v[80:83]
	v_mfma_f32_16x16x32_bf16 v[80:83], v[128:131], v[200:203], v[80:83]
	v_mfma_f32_16x16x32_bf16 v[72:75], v[148:151], v[196:199], v[72:75]
	v_mfma_f32_16x16x32_bf16 v[72:75], v[152:155], v[200:203], v[72:75]
	v_mfma_f32_16x16x32_bf16 v[76:79], v[140:143], v[196:199], v[76:79]
	v_mfma_f32_16x16x32_bf16 v[76:79], v[144:147], v[200:203], v[76:79]
	v_mfma_f32_16x16x32_bf16 v[68:71], v[156:159], v[196:199], v[68:71]
	v_mfma_f32_16x16x32_bf16 v[68:71], v[160:163], v[200:203], v[68:71]
	s_setprio 0
	s_barrier
	s_sleep 2
	s_add_i32 s16, s49, s2
	v_lshl_add_u64 v[204:205], v[204:205], 0, s[66:67]
	s_mov_b32 m0, s16
	ds_read_b128 v[164:167], v221 offset:49152
	ds_read_b128 v[168:171], v221 offset:50176
	ds_read_b128 v[172:175], v221 offset:51200
	ds_read_b128 v[176:179], v221 offset:52224
	ds_read_b128 v[180:183], v221 offset:53248
	ds_read_b128 v[184:187], v221 offset:54272
	ds_read_b128 v[196:199], v221 offset:55296
	ds_read_b128 v[200:203], v221 offset:56320
	global_load_lds_dwordx4 v[204:205], off
	s_add_i32 m0, s16, 0x2000
	s_add_u32 s16, s20, 0x160080
	v_lshl_add_u64 v[204:205], v[206:207], 0, s[66:67]
	s_addc_u32 s17, s21, 0
	s_add_i32 s20, s50, s2
	global_load_lds_dwordx4 v[204:205], off
	v_lshl_add_u64 v[204:205], s[16:17], 0, v[2:3]
	s_mov_b32 m0, s20
	s_nop 0
	global_load_lds_dwordx4 v[204:205], off
	v_lshl_add_u64 v[204:205], s[16:17], 0, v[190:191]
	s_add_i32 m0, s20, 0x2000
	s_nop 0
	global_load_lds_dwordx4 v[204:205], off
	v_lshl_add_u64 v[204:205], v[208:209], 0, s[66:67]
	s_mov_b32 m0, s34
	s_nop 0
	global_load_lds_dwordx4 v[204:205], off
	v_lshl_add_u64 v[204:205], v[210:211], 0, s[66:67]
	s_mov_b32 m0, s35
	s_nop 0
	global_load_lds_dwordx4 v[204:205], off
	s_waitcnt vmcnt(8)
	s_waitcnt lgkmcnt(0)
	s_barrier
	s_setprio 1
	s_waitcnt lgkmcnt(0)
	v_mfma_f32_16x16x32_bf16 v[64:67], v[124:127], v[164:167], v[64:67]
	v_mfma_f32_16x16x32_bf16 v[64:67], v[128:131], v[168:171], v[64:67]
	v_mfma_f32_16x16x32_bf16 v[56:59], v[148:151], v[164:167], v[56:59]
	v_mfma_f32_16x16x32_bf16 v[56:59], v[152:155], v[168:171], v[56:59]
	v_mfma_f32_16x16x32_bf16 v[60:63], v[140:143], v[164:167], v[60:63]
	v_mfma_f32_16x16x32_bf16 v[60:63], v[144:147], v[168:171], v[60:63]
	v_mfma_f32_16x16x32_bf16 v[52:55], v[156:159], v[164:167], v[52:55]
	v_mfma_f32_16x16x32_bf16 v[52:55], v[160:163], v[168:171], v[52:55]
	v_mfma_f32_16x16x32_bf16 v[48:51], v[124:127], v[172:175], v[48:51]
	v_mfma_f32_16x16x32_bf16 v[48:51], v[128:131], v[176:179], v[48:51]
	v_mfma_f32_16x16x32_bf16 v[40:43], v[148:151], v[172:175], v[40:43]
	v_mfma_f32_16x16x32_bf16 v[40:43], v[152:155], v[176:179], v[40:43]
	v_mfma_f32_16x16x32_bf16 v[44:47], v[140:143], v[172:175], v[44:47]
	v_mfma_f32_16x16x32_bf16 v[44:47], v[144:147], v[176:179], v[44:47]
	v_mfma_f32_16x16x32_bf16 v[36:39], v[156:159], v[172:175], v[36:39]
	v_mfma_f32_16x16x32_bf16 v[36:39], v[160:163], v[176:179], v[36:39]
	v_mfma_f32_16x16x32_bf16 v[32:35], v[124:127], v[180:183], v[32:35]
	v_mfma_f32_16x16x32_bf16 v[32:35], v[128:131], v[184:187], v[32:35]
	v_mfma_f32_16x16x32_bf16 v[24:27], v[148:151], v[180:183], v[24:27]
	v_mfma_f32_16x16x32_bf16 v[24:27], v[152:155], v[184:187], v[24:27]
	v_mfma_f32_16x16x32_bf16 v[28:31], v[140:143], v[180:183], v[28:31]
	v_mfma_f32_16x16x32_bf16 v[28:31], v[144:147], v[184:187], v[28:31]
	v_mfma_f32_16x16x32_bf16 v[20:23], v[156:159], v[180:183], v[20:23]
	v_mfma_f32_16x16x32_bf16 v[20:23], v[160:163], v[184:187], v[20:23]
	v_mfma_f32_16x16x32_bf16 v[16:19], v[124:127], v[196:199], v[16:19]
	v_mfma_f32_16x16x32_bf16 v[16:19], v[128:131], v[200:203], v[16:19]
	v_mfma_f32_16x16x32_bf16 v[8:11], v[148:151], v[196:199], v[8:11]
	v_mfma_f32_16x16x32_bf16 v[8:11], v[152:155], v[200:203], v[8:11]
	v_mfma_f32_16x16x32_bf16 v[12:15], v[140:143], v[196:199], v[12:15]
	v_mfma_f32_16x16x32_bf16 v[12:15], v[144:147], v[200:203], v[12:15]
	v_mfma_f32_16x16x32_bf16 v[4:7], v[156:159], v[196:199], v[4:7]
	v_mfma_f32_16x16x32_bf16 v[4:7], v[160:163], v[200:203], v[4:7]
	s_setprio 0
	s_barrier
	s_add_i32 s48, s48, 2
	s_add_u32 s40, s40, 0x100
	s_addc_u32 s41, s41, 0
	s_cmpk_gt_u32 s48, 0x55
	s_mov_b64 s[16:17], s[18:19]
	s_cbranch_scc0 .LBB0_301
	s_and_b64 vcc, exec, s[10:11]
	s_cbranch_vccz .LBB0_304
	s_barrier

.LBB0_347:
	s_sleep 2
	s_add_u32 s16, s14, 0x100
	s_addc_u32 s17, s15, 0
	s_add_i32 s44, 0, 0x10000
	s_cmpk_eq_i32 s43, 0x54
	s_cselect_b32 s21, s11, s17
	s_cselect_b32 s20, s10, s16
	s_cselect_b32 s19, s13, s39
	s_cselect_b32 s18, s12, s38
	s_add_i32 s45, 0, 0x14000
	v_add_u32_e32 v144, s44, v236
	v_add_u32_e32 v160, s45, v236
	ds_read_b128 v[132:135], v144
	ds_read_b128 v[136:139], v144 offset:1024
	ds_read_b128 v[140:143], v144 offset:2048
	ds_read_b128 v[144:147], v144 offset:3072
	ds_read_b128 v[148:151], v160
	ds_read_b128 v[152:155], v160 offset:1024
	ds_read_b128 v[156:159], v160 offset:2048
	ds_read_b128 v[160:163], v160 offset:3072
	v_lshl_add_u64 v[204:205], s[14:15], 0, v[200:201]
	s_add_i32 m0, s23, 0xc000
	ds_read_b128 v[164:167], v238
	ds_read_b128 v[168:171], v238 offset:1024
	ds_read_b128 v[172:175], v238 offset:2048
	ds_read_b128 v[176:179], v238 offset:3072
	ds_read_b128 v[180:183], v238 offset:4096
	ds_read_b128 v[184:187], v238 offset:5120
	ds_read_b128 v[188:191], v238 offset:6144
	ds_read_b128 v[192:195], v238 offset:7168
	global_load_lds_dwordx4 v[204:205], off
	v_lshl_add_u64 v[204:205], s[14:15], 0, v[202:203]
	s_add_i32 m0, s23, 0xe000
	s_nop 0
	global_load_lds_dwordx4 v[204:205], off
	s_waitcnt vmcnt(8)
	s_waitcnt lgkmcnt(0)
	s_barrier
	s_setprio 1
	s_waitcnt lgkmcnt(0)
	v_mfma_f32_16x16x32_bf16 v[128:131], v[132:135], v[164:167], v[128:131]
	v_mfma_f32_16x16x32_bf16 v[128:131], v[136:139], v[168:171], v[128:131]
	v_mfma_f32_16x16x32_bf16 v[120:123], v[148:151], v[164:167], v[120:123]
	v_mfma_f32_16x16x32_bf16 v[120:123], v[152:155], v[168:171], v[120:123]
	v_mfma_f32_16x16x32_bf16 v[124:127], v[140:143], v[164:167], v[124:127]
	v_mfma_f32_16x16x32_bf16 v[124:127], v[144:147], v[168:171], v[124:127]
	v_mfma_f32_16x16x32_bf16 v[112:115], v[156:159], v[164:167], v[112:115]
	v_mfma_f32_16x16x32_bf16 v[112:115], v[160:163], v[168:171], v[112:115]
	v_mfma_f32_16x16x32_bf16 v[116:119], v[132:135], v[172:175], v[116:119]
	v_mfma_f32_16x16x32_bf16 v[116:119], v[136:139], v[176:179], v[116:119]
	v_mfma_f32_16x16x32_bf16 v[104:107], v[148:151], v[172:175], v[104:107]
	v_mfma_f32_16x16x32_bf16 v[104:107], v[152:155], v[176:179], v[104:107]
	v_mfma_f32_16x16x32_bf16 v[108:111], v[140:143], v[172:175], v[108:111]
	v_mfma_f32_16x16x32_bf16 v[108:111], v[144:147], v[176:179], v[108:111]
	v_mfma_f32_16x16x32_bf16 v[96:99], v[156:159], v[172:175], v[96:99]
	v_mfma_f32_16x16x32_bf16 v[96:99], v[160:163], v[176:179], v[96:99]
	v_mfma_f32_16x16x32_bf16 v[100:103], v[132:135], v[180:183], v[100:103]
	v_mfma_f32_16x16x32_bf16 v[100:103], v[136:139], v[184:187], v[100:103]
	v_mfma_f32_16x16x32_bf16 v[88:91], v[148:151], v[180:183], v[88:91]
	v_mfma_f32_16x16x32_bf16 v[88:91], v[152:155], v[184:187], v[88:91]
	v_mfma_f32_16x16x32_bf16 v[92:95], v[140:143], v[180:183], v[92:95]
	v_mfma_f32_16x16x32_bf16 v[92:95], v[144:147], v[184:187], v[92:95]
	v_mfma_f32_16x16x32_bf16 v[80:83], v[156:159], v[180:183], v[80:83]
	v_mfma_f32_16x16x32_bf16 v[80:83], v[160:163], v[184:187], v[80:83]
	v_mfma_f32_16x16x32_bf16 v[84:87], v[132:135], v[188:191], v[84:87]
	v_mfma_f32_16x16x32_bf16 v[84:87], v[136:139], v[192:195], v[84:87]
	v_mfma_f32_16x16x32_bf16 v[72:75], v[148:151], v[188:191], v[72:75]
	v_mfma_f32_16x16x32_bf16 v[72:75], v[152:155], v[192:195], v[72:75]
	v_mfma_f32_16x16x32_bf16 v[76:79], v[140:143], v[188:191], v[76:79]
	v_mfma_f32_16x16x32_bf16 v[76:79], v[144:147], v[192:195], v[76:79]
	v_mfma_f32_16x16x32_bf16 v[68:71], v[156:159], v[188:191], v[68:71]
	v_mfma_f32_16x16x32_bf16 v[68:71], v[160:163], v[192:195], v[68:71]
	s_setprio 0
	s_barrier
	s_sleep 2
	s_add_i32 s14, s44, s22
	v_lshl_add_u64 v[204:205], s[18:19], 0, v[2:3]
	s_mov_b32 m0, s14
	ds_read_b128 v[164:167], v238 offset:16384
	ds_read_b128 v[168:171], v238 offset:17408
	ds_read_b128 v[172:175], v238 offset:18432
	ds_read_b128 v[176:179], v238 offset:19456
	ds_read_b128 v[180:183], v238 offset:20480
	ds_read_b128 v[184:187], v238 offset:21504
	ds_read_b128 v[188:191], v238 offset:22528
	ds_read_b128 v[192:195], v238 offset:23552
	global_load_lds_dwordx4 v[204:205], off
	s_add_i32 m0, s14, 0x2000
	s_add_u32 s14, s18, 0x160000
	v_lshl_add_u64 v[206:207], s[18:19], 0, v[198:199]
	s_addc_u32 s15, s19, 0
	s_add_i32 s44, s45, s22
	global_load_lds_dwordx4 v[206:207], off
	v_lshl_add_u64 v[208:209], s[14:15], 0, v[2:3]
	s_mov_b32 m0, s44
	v_lshl_add_u64 v[210:211], s[20:21], 0, v[196:197]
	global_load_lds_dwordx4 v[208:209], off
	v_lshl_add_u64 v[208:209], s[14:15], 0, v[198:199]
	s_add_i32 m0, s44, 0x2000
	s_nop 0
	global_load_lds_dwordx4 v[208:209], off
	v_lshl_add_u64 v[208:209], s[20:21], 0, v[0:1]
	s_mov_b32 m0, s23
	s_nop 0
	global_load_lds_dwordx4 v[208:209], off
	s_mov_b32 m0, s28
	s_nop 0
	global_load_lds_dwordx4 v[210:211], off
	s_waitcnt vmcnt(8)
	s_waitcnt lgkmcnt(0)
	s_barrier
	s_setprio 1
	s_waitcnt lgkmcnt(0)
	v_mfma_f32_16x16x32_bf16 v[64:67], v[132:135], v[164:167], v[64:67]
	v_mfma_f32_16x16x32_bf16 v[64:67], v[136:139], v[168:171], v[64:67]
	v_mfma_f32_16x16x32_bf16 v[56:59], v[148:151], v[164:167], v[56:59]
	v_mfma_f32_16x16x32_bf16 v[56:59], v[152:155], v[168:171], v[56:59]
	v_mfma_f32_16x16x32_bf16 v[60:63], v[140:143], v[164:167], v[60:63]
	v_mfma_f32_16x16x32_bf16 v[60:63], v[144:147], v[168:171], v[60:63]
	v_mfma_f32_16x16x32_bf16 v[48:51], v[156:159], v[164:167], v[48:51]
	v_mfma_f32_16x16x32_bf16 v[48:51], v[160:163], v[168:171], v[48:51]
	v_mfma_f32_16x16x32_bf16 v[52:55], v[132:135], v[172:175], v[52:55]
	v_mfma_f32_16x16x32_bf16 v[52:55], v[136:139], v[176:179], v[52:55]
	v_mfma_f32_16x16x32_bf16 v[40:43], v[148:151], v[172:175], v[40:43]
	v_mfma_f32_16x16x32_bf16 v[40:43], v[152:155], v[176:179], v[40:43]
	v_mfma_f32_16x16x32_bf16 v[44:47], v[140:143], v[172:175], v[44:47]
	v_mfma_f32_16x16x32_bf16 v[44:47], v[144:147], v[176:179], v[44:47]
	v_mfma_f32_16x16x32_bf16 v[32:35], v[156:159], v[172:175], v[32:35]
	v_mfma_f32_16x16x32_bf16 v[32:35], v[160:163], v[176:179], v[32:35]
	v_mfma_f32_16x16x32_bf16 v[36:39], v[132:135], v[180:183], v[36:39]
	v_mfma_f32_16x16x32_bf16 v[36:39], v[136:139], v[184:187], v[36:39]
	v_mfma_f32_16x16x32_bf16 v[24:27], v[148:151], v[180:183], v[24:27]
	v_mfma_f32_16x16x32_bf16 v[24:27], v[152:155], v[184:187], v[24:27]
	v_mfma_f32_16x16x32_bf16 v[28:31], v[140:143], v[180:183], v[28:31]
	v_mfma_f32_16x16x32_bf16 v[28:31], v[144:147], v[184:187], v[28:31]
	v_mfma_f32_16x16x32_bf16 v[16:19], v[156:159], v[180:183], v[16:19]
	v_mfma_f32_16x16x32_bf16 v[16:19], v[160:163], v[184:187], v[16:19]
	v_mfma_f32_16x16x32_bf16 v[20:23], v[132:135], v[188:191], v[20:23]
	v_mfma_f32_16x16x32_bf16 v[20:23], v[136:139], v[192:195], v[20:23]
	v_mfma_f32_16x16x32_bf16 v[8:11], v[148:151], v[188:191], v[8:11]
	v_mfma_f32_16x16x32_bf16 v[8:11], v[152:155], v[192:195], v[8:11]
	v_mfma_f32_16x16x32_bf16 v[12:15], v[140:143], v[188:191], v[12:15]
	v_mfma_f32_16x16x32_bf16 v[12:15], v[144:147], v[192:195], v[12:15]
	v_mfma_f32_16x16x32_bf16 v[4:7], v[156:159], v[188:191], v[4:7]
	v_mfma_f32_16x16x32_bf16 v[4:7], v[160:163], v[192:195], v[4:7]
	s_setprio 0
	s_barrier
	s_sleep 2
	s_add_i32 s44, 0, 0x18000
	s_add_i32 s45, 0, 0x1c000
	v_add_u32_e32 v144, s44, v236
	v_add_u32_e32 v160, s45, v236
	ds_read_b128 v[132:135], v144
	ds_read_b128 v[136:139], v144 offset:1024
	ds_read_b128 v[140:143], v144 offset:2048
	ds_read_b128 v[144:147], v144 offset:3072
	ds_read_b128 v[148:151], v160
	ds_read_b128 v[152:155], v160 offset:1024
	ds_read_b128 v[156:159], v160 offset:2048
	ds_read_b128 v[160:163], v160 offset:3072
	s_add_u32 s14, s20, 0x160000
	s_addc_u32 s15, s21, 0
	s_mov_b32 m0, s29
	v_lshl_add_u64 v[212:213], s[14:15], 0, v[0:1]
	ds_read_b128 v[164:167], v238 offset:32768
	ds_read_b128 v[168:171], v238 offset:33792
	ds_read_b128 v[172:175], v238 offset:34816
	ds_read_b128 v[176:179], v238 offset:35840
	ds_read_b128 v[180:183], v238 offset:36864
	ds_read_b128 v[184:187], v238 offset:37888
	ds_read_b128 v[188:191], v238 offset:38912
	ds_read_b128 v[192:195], v238 offset:39936
	global_load_lds_dwordx4 v[212:213], off
	v_lshl_add_u64 v[212:213], s[14:15], 0, v[196:197]
	s_mov_b32 m0, s30
	s_nop 0
	global_load_lds_dwordx4 v[212:213], off
	s_waitcnt vmcnt(8)
	s_waitcnt lgkmcnt(0)
	s_barrier
	s_setprio 1
	s_waitcnt lgkmcnt(0)
	v_mfma_f32_16x16x32_bf16 v[128:131], v[132:135], v[164:167], v[128:131]
	v_mfma_f32_16x16x32_bf16 v[128:131], v[136:139], v[168:171], v[128:131]
	v_mfma_f32_16x16x32_bf16 v[120:123], v[148:151], v[164:167], v[120:123]
	v_mfma_f32_16x16x32_bf16 v[120:123], v[152:155], v[168:171], v[120:123]
	v_mfma_f32_16x16x32_bf16 v[124:127], v[140:143], v[164:167], v[124:127]
	v_mfma_f32_16x16x32_bf16 v[124:127], v[144:147], v[168:171], v[124:127]
	v_mfma_f32_16x16x32_bf16 v[112:115], v[156:159], v[164:167], v[112:115]
	v_mfma_f32_16x16x32_bf16 v[112:115], v[160:163], v[168:171], v[112:115]
	v_mfma_f32_16x16x32_bf16 v[116:119], v[132:135], v[172:175], v[116:119]
	v_mfma_f32_16x16x32_bf16 v[116:119], v[136:139], v[176:179], v[116:119]
	v_mfma_f32_16x16x32_bf16 v[104:107], v[148:151], v[172:175], v[104:107]
	v_mfma_f32_16x16x32_bf16 v[104:107], v[152:155], v[176:179], v[104:107]
	v_mfma_f32_16x16x32_bf16 v[108:111], v[140:143], v[172:175], v[108:111]
	v_mfma_f32_16x16x32_bf16 v[108:111], v[144:147], v[176:179], v[108:111]
	v_mfma_f32_16x16x32_bf16 v[96:99], v[156:159], v[172:175], v[96:99]
	v_mfma_f32_16x16x32_bf16 v[96:99], v[160:163], v[176:179], v[96:99]
	v_mfma_f32_16x16x32_bf16 v[100:103], v[132:135], v[180:183], v[100:103]
	v_mfma_f32_16x16x32_bf16 v[100:103], v[136:139], v[184:187], v[100:103]
	v_mfma_f32_16x16x32_bf16 v[88:91], v[148:151], v[180:183], v[88:91]
	v_mfma_f32_16x16x32_bf16 v[88:91], v[152:155], v[184:187], v[88:91]
	v_mfma_f32_16x16x32_bf16 v[92:95], v[140:143], v[180:183], v[92:95]
	v_mfma_f32_16x16x32_bf16 v[92:95], v[144:147], v[184:187], v[92:95]
	v_mfma_f32_16x16x32_bf16 v[80:83], v[156:159], v[180:183], v[80:83]
	v_mfma_f32_16x16x32_bf16 v[80:83], v[160:163], v[184:187], v[80:83]
	v_mfma_f32_16x16x32_bf16 v[84:87], v[132:135], v[188:191], v[84:87]
	v_mfma_f32_16x16x32_bf16 v[84:87], v[136:139], v[192:195], v[84:87]
	v_mfma_f32_16x16x32_bf16 v[72:75], v[148:151], v[188:191], v[72:75]
	v_mfma_f32_16x16x32_bf16 v[72:75], v[152:155], v[192:195], v[72:75]
	v_mfma_f32_16x16x32_bf16 v[76:79], v[140:143], v[188:191], v[76:79]
	v_mfma_f32_16x16x32_bf16 v[76:79], v[144:147], v[192:195], v[76:79]
	v_mfma_f32_16x16x32_bf16 v[68:71], v[156:159], v[188:191], v[68:71]
	v_mfma_f32_16x16x32_bf16 v[68:71], v[160:163], v[192:195], v[68:71]
	s_setprio 0
	s_barrier
	s_sleep 2
	s_add_i32 s14, s44, s22
	v_lshl_add_u64 v[204:205], v[204:205], 0, s[66:67]
	s_mov_b32 m0, s14
	ds_read_b128 v[164:167], v238 offset:49152
	ds_read_b128 v[168:171], v238 offset:50176
	ds_read_b128 v[172:175], v238 offset:51200
	ds_read_b128 v[176:179], v238 offset:52224
	ds_read_b128 v[180:183], v238 offset:53248
	ds_read_b128 v[184:187], v238 offset:54272
	ds_read_b128 v[188:191], v238 offset:55296
	ds_read_b128 v[192:195], v238 offset:56320
	global_load_lds_dwordx4 v[204:205], off
	s_add_i32 m0, s14, 0x2000
	s_add_u32 s14, s18, 0x160080
	v_lshl_add_u64 v[204:205], v[206:207], 0, s[66:67]
	s_addc_u32 s15, s19, 0
	s_add_i32 s18, s45, s22
	global_load_lds_dwordx4 v[204:205], off
	v_lshl_add_u64 v[204:205], s[14:15], 0, v[2:3]
	s_mov_b32 m0, s18
	s_nop 0
	global_load_lds_dwordx4 v[204:205], off
	v_lshl_add_u64 v[204:205], s[14:15], 0, v[198:199]
	s_add_i32 m0, s18, 0x2000
	s_nop 0
	global_load_lds_dwordx4 v[204:205], off
	v_lshl_add_u64 v[204:205], v[208:209], 0, s[66:67]
	s_mov_b32 m0, s31
	s_nop 0
	global_load_lds_dwordx4 v[204:205], off
	v_lshl_add_u64 v[204:205], v[210:211], 0, s[66:67]
	s_mov_b32 m0, s34
	s_nop 0
	global_load_lds_dwordx4 v[204:205], off
	s_waitcnt vmcnt(8)
	s_waitcnt lgkmcnt(0)
	s_barrier
	s_setprio 1
	s_waitcnt lgkmcnt(0)
	v_mfma_f32_16x16x32_bf16 v[64:67], v[132:135], v[164:167], v[64:67]
	v_mfma_f32_16x16x32_bf16 v[64:67], v[136:139], v[168:171], v[64:67]
	v_mfma_f32_16x16x32_bf16 v[56:59], v[148:151], v[164:167], v[56:59]
	v_mfma_f32_16x16x32_bf16 v[56:59], v[152:155], v[168:171], v[56:59]
	v_mfma_f32_16x16x32_bf16 v[60:63], v[140:143], v[164:167], v[60:63]
	v_mfma_f32_16x16x32_bf16 v[60:63], v[144:147], v[168:171], v[60:63]
	v_mfma_f32_16x16x32_bf16 v[48:51], v[156:159], v[164:167], v[48:51]
	v_mfma_f32_16x16x32_bf16 v[48:51], v[160:163], v[168:171], v[48:51]
	v_mfma_f32_16x16x32_bf16 v[52:55], v[132:135], v[172:175], v[52:55]
	v_mfma_f32_16x16x32_bf16 v[52:55], v[136:139], v[176:179], v[52:55]
	v_mfma_f32_16x16x32_bf16 v[40:43], v[148:151], v[172:175], v[40:43]
	v_mfma_f32_16x16x32_bf16 v[40:43], v[152:155], v[176:179], v[40:43]
	v_mfma_f32_16x16x32_bf16 v[44:47], v[140:143], v[172:175], v[44:47]
	v_mfma_f32_16x16x32_bf16 v[44:47], v[144:147], v[176:179], v[44:47]
	v_mfma_f32_16x16x32_bf16 v[32:35], v[156:159], v[172:175], v[32:35]
	v_mfma_f32_16x16x32_bf16 v[32:35], v[160:163], v[176:179], v[32:35]
	v_mfma_f32_16x16x32_bf16 v[36:39], v[132:135], v[180:183], v[36:39]
	v_mfma_f32_16x16x32_bf16 v[36:39], v[136:139], v[184:187], v[36:39]
	v_mfma_f32_16x16x32_bf16 v[24:27], v[148:151], v[180:183], v[24:27]
	v_mfma_f32_16x16x32_bf16 v[24:27], v[152:155], v[184:187], v[24:27]
	v_mfma_f32_16x16x32_bf16 v[28:31], v[140:143], v[180:183], v[28:31]
	v_mfma_f32_16x16x32_bf16 v[28:31], v[144:147], v[184:187], v[28:31]
	v_mfma_f32_16x16x32_bf16 v[16:19], v[156:159], v[180:183], v[16:19]
	v_mfma_f32_16x16x32_bf16 v[16:19], v[160:163], v[184:187], v[16:19]
	v_mfma_f32_16x16x32_bf16 v[20:23], v[132:135], v[188:191], v[20:23]
	v_mfma_f32_16x16x32_bf16 v[20:23], v[136:139], v[192:195], v[20:23]
	v_mfma_f32_16x16x32_bf16 v[8:11], v[148:151], v[188:191], v[8:11]
	v_mfma_f32_16x16x32_bf16 v[8:11], v[152:155], v[192:195], v[8:11]
	v_mfma_f32_16x16x32_bf16 v[12:15], v[140:143], v[188:191], v[12:15]
	v_mfma_f32_16x16x32_bf16 v[12:15], v[144:147], v[192:195], v[12:15]
	v_mfma_f32_16x16x32_bf16 v[4:7], v[156:159], v[188:191], v[4:7]
	v_mfma_f32_16x16x32_bf16 v[4:7], v[160:163], v[192:195], v[4:7]
	s_setprio 0
	s_barrier
	s_add_i32 s43, s43, 2
	s_add_u32 s38, s38, 0x100
	s_addc_u32 s39, s39, 0
	s_cmpk_gt_u32 s43, 0x55
	s_mov_b64 s[14:15], s[16:17]
	s_cbranch_scc0 .LBB0_347
	s_and_b64 vcc, exec, s[6:7]
	s_cbranch_vccz .LBB0_350
	s_barrier

.LBB0_430:
	s_sleep 2
	s_add_u32 s30, s28, 0xfff80080
	s_addc_u32 s31, s29, -1
	s_add_i32 s70, 0, 0x10000
	s_cmp_eq_u32 s69, 28
	s_cselect_b32 s43, s5, s31
	s_cselect_b32 s42, s23, s30
	s_cselect_b32 s31, s21, s68
	s_cselect_b32 s30, s62, s63
	s_add_i32 s73, 0, 0x14000
	s_waitcnt lgkmcnt(0)
	v_add_u32_e32 v152, s70, v163
	v_add_u32_e32 v160, s73, v163
	ds_read_b128 v[132:135], v152
	ds_read_b128 v[136:139], v152 offset:1024
	ds_read_b128 v[148:151], v152 offset:2048
	ds_read_b128 v[152:155], v152 offset:3072
	ds_read_b128 v[156:159], v160
	ds_read_b128 v[170:173], v160 offset:1024
	ds_read_b128 v[174:177], v160 offset:2048
	ds_read_b128 v[178:181], v160 offset:3072
	v_lshl_add_u64 v[160:161], s[28:29], 0, v[144:145]
	s_add_i32 m0, s15, 0xc000
	ds_read_b128 v[182:185], v167
	ds_read_b128 v[186:189], v167 offset:1024
	ds_read_b128 v[190:193], v167 offset:2048
	ds_read_b128 v[194:197], v167 offset:3072
	ds_read_b128 v[198:201], v167 offset:4096
	ds_read_b128 v[208:211], v167 offset:5120
	ds_read_b128 v[212:215], v167 offset:6144
	ds_read_b128 v[216:219], v167 offset:7168
	global_load_lds_dwordx4 v[160:161], off
	v_lshl_add_u64 v[160:161], s[28:29], 0, v[146:147]
	s_add_i32 m0, s15, 0xe000
	s_nop 0
	global_load_lds_dwordx4 v[160:161], off
	s_waitcnt vmcnt(8)
	s_waitcnt lgkmcnt(0)
	s_barrier
	s_setprio 1
	s_waitcnt lgkmcnt(0)
	v_mfma_f32_16x16x32_bf16 v[128:131], v[132:135], v[182:185], v[128:131]
	v_mfma_f32_16x16x32_bf16 v[128:131], v[136:139], v[186:189], v[128:131]
	v_mfma_f32_16x16x32_bf16 v[116:119], v[156:159], v[182:185], v[116:119]
	v_mfma_f32_16x16x32_bf16 v[116:119], v[170:173], v[186:189], v[116:119]
	v_mfma_f32_16x16x32_bf16 v[124:127], v[148:151], v[182:185], v[124:127]
	v_mfma_f32_16x16x32_bf16 v[124:127], v[152:155], v[186:189], v[124:127]
	v_mfma_f32_16x16x32_bf16 v[108:111], v[174:177], v[182:185], v[108:111]
	v_mfma_f32_16x16x32_bf16 v[108:111], v[178:181], v[186:189], v[108:111]
	v_mfma_f32_16x16x32_bf16 v[120:123], v[132:135], v[190:193], v[120:123]
	v_mfma_f32_16x16x32_bf16 v[120:123], v[136:139], v[194:197], v[120:123]
	v_mfma_f32_16x16x32_bf16 v[100:103], v[156:159], v[190:193], v[100:103]
	v_mfma_f32_16x16x32_bf16 v[100:103], v[170:173], v[194:197], v[100:103]
	v_mfma_f32_16x16x32_bf16 v[112:115], v[148:151], v[190:193], v[112:115]
	v_mfma_f32_16x16x32_bf16 v[112:115], v[152:155], v[194:197], v[112:115]
	v_mfma_f32_16x16x32_bf16 v[92:95], v[174:177], v[190:193], v[92:95]
	v_mfma_f32_16x16x32_bf16 v[92:95], v[178:181], v[194:197], v[92:95]
	v_mfma_f32_16x16x32_bf16 v[104:107], v[132:135], v[198:201], v[104:107]
	v_mfma_f32_16x16x32_bf16 v[104:107], v[136:139], v[208:211], v[104:107]
	v_mfma_f32_16x16x32_bf16 v[84:87], v[156:159], v[198:201], v[84:87]
	v_mfma_f32_16x16x32_bf16 v[84:87], v[170:173], v[208:211], v[84:87]
	v_mfma_f32_16x16x32_bf16 v[96:99], v[148:151], v[198:201], v[96:99]
	v_mfma_f32_16x16x32_bf16 v[96:99], v[152:155], v[208:211], v[96:99]
	v_mfma_f32_16x16x32_bf16 v[76:79], v[174:177], v[198:201], v[76:79]
	v_mfma_f32_16x16x32_bf16 v[76:79], v[178:181], v[208:211], v[76:79]
	v_mfma_f32_16x16x32_bf16 v[88:91], v[132:135], v[212:215], v[88:91]
	v_mfma_f32_16x16x32_bf16 v[88:91], v[136:139], v[216:219], v[88:91]
	v_mfma_f32_16x16x32_bf16 v[72:75], v[156:159], v[212:215], v[72:75]
	v_mfma_f32_16x16x32_bf16 v[72:75], v[170:173], v[216:219], v[72:75]
	v_mfma_f32_16x16x32_bf16 v[80:83], v[148:151], v[212:215], v[80:83]
	v_mfma_f32_16x16x32_bf16 v[80:83], v[152:155], v[216:219], v[80:83]
	v_mfma_f32_16x16x32_bf16 v[68:71], v[174:177], v[212:215], v[68:71]
	v_mfma_f32_16x16x32_bf16 v[68:71], v[178:181], v[216:219], v[68:71]
	s_setprio 0
	s_barrier
	s_sleep 2
	s_add_i32 s70, s70, s0
	v_lshl_add_u64 v[160:161], s[30:31], 0, v[2:3]
	s_mov_b32 m0, s70
	ds_read_b128 v[182:185], v167 offset:16384
	ds_read_b128 v[186:189], v167 offset:17408
	ds_read_b128 v[190:193], v167 offset:18432
	ds_read_b128 v[194:197], v167 offset:19456
	ds_read_b128 v[198:201], v167 offset:20480
	ds_read_b128 v[208:211], v167 offset:21504
	ds_read_b128 v[212:215], v167 offset:22528
	ds_read_b128 v[216:219], v167 offset:23552
	global_load_lds_dwordx4 v[160:161], off
	s_add_i32 m0, s70, 0x2000
	s_add_u32 s70, s30, 0x80000
	v_lshl_add_u64 v[202:203], s[30:31], 0, v[142:143]
	s_addc_u32 s71, s31, 0
	s_add_i32 s73, s73, s0
	global_load_lds_dwordx4 v[202:203], off
	v_lshl_add_u64 v[204:205], s[70:71], 0, v[2:3]
	s_mov_b32 m0, s73
	v_lshl_add_u64 v[206:207], s[42:43], 0, v[140:141]
	global_load_lds_dwordx4 v[204:205], off
	v_lshl_add_u64 v[204:205], s[70:71], 0, v[142:143]
	s_add_i32 m0, s73, 0x2000
	s_nop 0
	global_load_lds_dwordx4 v[204:205], off
	v_lshl_add_u64 v[204:205], s[42:43], 0, v[0:1]
	s_mov_b32 m0, s15
	s_nop 0
	global_load_lds_dwordx4 v[204:205], off
	s_mov_b32 m0, s53
	s_nop 0
	global_load_lds_dwordx4 v[206:207], off
	s_waitcnt vmcnt(8)
	s_waitcnt lgkmcnt(0)
	s_barrier
	s_setprio 1
	s_waitcnt lgkmcnt(0)
	v_mfma_f32_16x16x32_bf16 v[64:67], v[132:135], v[182:185], v[64:67]
	v_mfma_f32_16x16x32_bf16 v[64:67], v[136:139], v[186:189], v[64:67]
	v_mfma_f32_16x16x32_bf16 v[52:55], v[156:159], v[182:185], v[52:55]
	v_mfma_f32_16x16x32_bf16 v[52:55], v[170:173], v[186:189], v[52:55]
	v_mfma_f32_16x16x32_bf16 v[60:63], v[148:151], v[182:185], v[60:63]
	v_mfma_f32_16x16x32_bf16 v[60:63], v[152:155], v[186:189], v[60:63]
	v_mfma_f32_16x16x32_bf16 v[44:47], v[174:177], v[182:185], v[44:47]
	v_mfma_f32_16x16x32_bf16 v[44:47], v[178:181], v[186:189], v[44:47]
	v_mfma_f32_16x16x32_bf16 v[56:59], v[132:135], v[190:193], v[56:59]
	v_mfma_f32_16x16x32_bf16 v[56:59], v[136:139], v[194:197], v[56:59]
	v_mfma_f32_16x16x32_bf16 v[36:39], v[156:159], v[190:193], v[36:39]
	v_mfma_f32_16x16x32_bf16 v[36:39], v[170:173], v[194:197], v[36:39]
	v_mfma_f32_16x16x32_bf16 v[48:51], v[148:151], v[190:193], v[48:51]
	v_mfma_f32_16x16x32_bf16 v[48:51], v[152:155], v[194:197], v[48:51]
	v_mfma_f32_16x16x32_bf16 v[28:31], v[174:177], v[190:193], v[28:31]
	v_mfma_f32_16x16x32_bf16 v[28:31], v[178:181], v[194:197], v[28:31]
	v_mfma_f32_16x16x32_bf16 v[40:43], v[132:135], v[198:201], v[40:43]
	v_mfma_f32_16x16x32_bf16 v[40:43], v[136:139], v[208:211], v[40:43]
	v_mfma_f32_16x16x32_bf16 v[20:23], v[156:159], v[198:201], v[20:23]
	v_mfma_f32_16x16x32_bf16 v[20:23], v[170:173], v[208:211], v[20:23]
	v_mfma_f32_16x16x32_bf16 v[32:35], v[148:151], v[198:201], v[32:35]
	v_mfma_f32_16x16x32_bf16 v[32:35], v[152:155], v[208:211], v[32:35]
	v_mfma_f32_16x16x32_bf16 v[12:15], v[174:177], v[198:201], v[12:15]
	v_mfma_f32_16x16x32_bf16 v[12:15], v[178:181], v[208:211], v[12:15]
	v_mfma_f32_16x16x32_bf16 v[24:27], v[132:135], v[212:215], v[24:27]
	v_mfma_f32_16x16x32_bf16 v[24:27], v[136:139], v[216:219], v[24:27]
	v_mfma_f32_16x16x32_bf16 v[8:11], v[156:159], v[212:215], v[8:11]
	v_mfma_f32_16x16x32_bf16 v[8:11], v[170:173], v[216:219], v[8:11]
	v_mfma_f32_16x16x32_bf16 v[16:19], v[148:151], v[212:215], v[16:19]
	v_mfma_f32_16x16x32_bf16 v[16:19], v[152:155], v[216:219], v[16:19]
	v_mfma_f32_16x16x32_bf16 v[4:7], v[174:177], v[212:215], v[4:7]
	v_mfma_f32_16x16x32_bf16 v[4:7], v[178:181], v[216:219], v[4:7]
	s_setprio 0
	s_barrier
	s_sleep 2
	s_add_i32 s70, 0, 0x18000
	s_add_i32 s71, 0, 0x1c000
	v_add_u32_e32 v152, s70, v163
	v_add_u32_e32 v178, s71, v163
	ds_read_b128 v[132:135], v152
	ds_read_b128 v[136:139], v152 offset:1024
	ds_read_b128 v[148:151], v152 offset:2048
	ds_read_b128 v[152:155], v152 offset:3072
	ds_read_b128 v[156:159], v178
	ds_read_b128 v[170:173], v178 offset:1024
	ds_read_b128 v[174:177], v178 offset:2048
	ds_read_b128 v[178:181], v178 offset:3072
	s_add_u32 s42, s42, 0x80000
	s_addc_u32 s43, s43, 0
	s_mov_b32 m0, s54
	v_lshl_add_u64 v[220:221], s[42:43], 0, v[0:1]
	ds_read_b128 v[182:185], v167 offset:32768
	ds_read_b128 v[186:189], v167 offset:33792
	ds_read_b128 v[190:193], v167 offset:34816
	ds_read_b128 v[194:197], v167 offset:35840
	ds_read_b128 v[198:201], v167 offset:36864
	ds_read_b128 v[208:211], v167 offset:37888
	ds_read_b128 v[212:215], v167 offset:38912
	ds_read_b128 v[216:219], v167 offset:39936
	global_load_lds_dwordx4 v[220:221], off
	v_lshl_add_u64 v[220:221], s[42:43], 0, v[140:141]
	s_mov_b32 m0, s55
	s_nop 0
	global_load_lds_dwordx4 v[220:221], off
	s_waitcnt vmcnt(8)
	s_waitcnt lgkmcnt(0)
	s_barrier
	s_setprio 1
	s_waitcnt lgkmcnt(0)
	v_mfma_f32_16x16x32_bf16 v[128:131], v[132:135], v[182:185], v[128:131]
	v_mfma_f32_16x16x32_bf16 v[128:131], v[136:139], v[186:189], v[128:131]
	v_mfma_f32_16x16x32_bf16 v[116:119], v[156:159], v[182:185], v[116:119]
	v_mfma_f32_16x16x32_bf16 v[116:119], v[170:173], v[186:189], v[116:119]
	v_mfma_f32_16x16x32_bf16 v[124:127], v[148:151], v[182:185], v[124:127]
	v_mfma_f32_16x16x32_bf16 v[124:127], v[152:155], v[186:189], v[124:127]
	v_mfma_f32_16x16x32_bf16 v[108:111], v[174:177], v[182:185], v[108:111]
	v_mfma_f32_16x16x32_bf16 v[108:111], v[178:181], v[186:189], v[108:111]
	v_mfma_f32_16x16x32_bf16 v[120:123], v[132:135], v[190:193], v[120:123]
	v_mfma_f32_16x16x32_bf16 v[120:123], v[136:139], v[194:197], v[120:123]
	v_mfma_f32_16x16x32_bf16 v[100:103], v[156:159], v[190:193], v[100:103]
	v_mfma_f32_16x16x32_bf16 v[100:103], v[170:173], v[194:197], v[100:103]
	v_mfma_f32_16x16x32_bf16 v[112:115], v[148:151], v[190:193], v[112:115]
	v_mfma_f32_16x16x32_bf16 v[112:115], v[152:155], v[194:197], v[112:115]
	v_mfma_f32_16x16x32_bf16 v[92:95], v[174:177], v[190:193], v[92:95]
	v_mfma_f32_16x16x32_bf16 v[92:95], v[178:181], v[194:197], v[92:95]
	v_mfma_f32_16x16x32_bf16 v[104:107], v[132:135], v[198:201], v[104:107]
	v_mfma_f32_16x16x32_bf16 v[104:107], v[136:139], v[208:211], v[104:107]
	v_mfma_f32_16x16x32_bf16 v[84:87], v[156:159], v[198:201], v[84:87]
	v_mfma_f32_16x16x32_bf16 v[84:87], v[170:173], v[208:211], v[84:87]
	v_mfma_f32_16x16x32_bf16 v[96:99], v[148:151], v[198:201], v[96:99]
	v_mfma_f32_16x16x32_bf16 v[96:99], v[152:155], v[208:211], v[96:99]
	v_mfma_f32_16x16x32_bf16 v[76:79], v[174:177], v[198:201], v[76:79]
	v_mfma_f32_16x16x32_bf16 v[76:79], v[178:181], v[208:211], v[76:79]
	v_mfma_f32_16x16x32_bf16 v[88:91], v[132:135], v[212:215], v[88:91]
	v_mfma_f32_16x16x32_bf16 v[88:91], v[136:139], v[216:219], v[88:91]
	v_mfma_f32_16x16x32_bf16 v[72:75], v[156:159], v[212:215], v[72:75]
	v_mfma_f32_16x16x32_bf16 v[72:75], v[170:173], v[216:219], v[72:75]
	v_mfma_f32_16x16x32_bf16 v[80:83], v[148:151], v[212:215], v[80:83]
	v_mfma_f32_16x16x32_bf16 v[80:83], v[152:155], v[216:219], v[80:83]
	v_mfma_f32_16x16x32_bf16 v[68:71], v[174:177], v[212:215], v[68:71]
	v_mfma_f32_16x16x32_bf16 v[68:71], v[178:181], v[216:219], v[68:71]
	s_setprio 0
	s_barrier
	s_sleep 2
	s_add_i32 s42, s70, s0
	v_lshl_add_u64 v[160:161], v[160:161], 0, s[66:67]
	s_mov_b32 m0, s42
	ds_read_b128 v[182:185], v167 offset:49152
	ds_read_b128 v[186:189], v167 offset:50176
	ds_read_b128 v[190:193], v167 offset:51200
	ds_read_b128 v[194:197], v167 offset:52224
	ds_read_b128 v[198:201], v167 offset:53248
	ds_read_b128 v[208:211], v167 offset:54272
	ds_read_b128 v[212:215], v167 offset:55296
	ds_read_b128 v[216:219], v167 offset:56320
	global_load_lds_dwordx4 v[160:161], off
	s_add_i32 m0, s42, 0x2000
	s_add_u32 s30, s30, 0x80080
	v_lshl_add_u64 v[160:161], v[202:203], 0, s[66:67]
	s_addc_u32 s31, s31, 0
	s_add_i32 s42, s71, s0
	global_load_lds_dwordx4 v[160:161], off
	v_lshl_add_u64 v[160:161], s[30:31], 0, v[2:3]
	s_mov_b32 m0, s42
	s_nop 0
	global_load_lds_dwordx4 v[160:161], off
	v_lshl_add_u64 v[160:161], s[30:31], 0, v[142:143]
	s_add_i32 m0, s42, 0x2000
	s_nop 0
	global_load_lds_dwordx4 v[160:161], off
	v_lshl_add_u64 v[160:161], v[204:205], 0, s[66:67]
	s_mov_b32 m0, s60
	s_nop 0
	global_load_lds_dwordx4 v[160:161], off
	v_lshl_add_u64 v[160:161], v[206:207], 0, s[66:67]
	s_mov_b32 m0, s64
	s_nop 0
	global_load_lds_dwordx4 v[160:161], off
	s_waitcnt vmcnt(8)
	s_waitcnt lgkmcnt(0)
	s_barrier
	s_setprio 1
	s_waitcnt lgkmcnt(0)
	v_mfma_f32_16x16x32_bf16 v[64:67], v[132:135], v[182:185], v[64:67]
	v_mfma_f32_16x16x32_bf16 v[64:67], v[136:139], v[186:189], v[64:67]
	v_mfma_f32_16x16x32_bf16 v[52:55], v[156:159], v[182:185], v[52:55]
	v_mfma_f32_16x16x32_bf16 v[52:55], v[170:173], v[186:189], v[52:55]
	v_mfma_f32_16x16x32_bf16 v[60:63], v[148:151], v[182:185], v[60:63]
	v_mfma_f32_16x16x32_bf16 v[60:63], v[152:155], v[186:189], v[60:63]
	v_mfma_f32_16x16x32_bf16 v[44:47], v[174:177], v[182:185], v[44:47]
	v_mfma_f32_16x16x32_bf16 v[44:47], v[178:181], v[186:189], v[44:47]
	v_mfma_f32_16x16x32_bf16 v[56:59], v[132:135], v[190:193], v[56:59]
	v_mfma_f32_16x16x32_bf16 v[56:59], v[136:139], v[194:197], v[56:59]
	v_mfma_f32_16x16x32_bf16 v[36:39], v[156:159], v[190:193], v[36:39]
	v_mfma_f32_16x16x32_bf16 v[36:39], v[170:173], v[194:197], v[36:39]
	v_mfma_f32_16x16x32_bf16 v[48:51], v[148:151], v[190:193], v[48:51]
	v_mfma_f32_16x16x32_bf16 v[48:51], v[152:155], v[194:197], v[48:51]
	v_mfma_f32_16x16x32_bf16 v[28:31], v[174:177], v[190:193], v[28:31]
	v_mfma_f32_16x16x32_bf16 v[28:31], v[178:181], v[194:197], v[28:31]
	v_mfma_f32_16x16x32_bf16 v[40:43], v[132:135], v[198:201], v[40:43]
	v_mfma_f32_16x16x32_bf16 v[40:43], v[136:139], v[208:211], v[40:43]
	v_mfma_f32_16x16x32_bf16 v[20:23], v[156:159], v[198:201], v[20:23]
	v_mfma_f32_16x16x32_bf16 v[20:23], v[170:173], v[208:211], v[20:23]
	v_mfma_f32_16x16x32_bf16 v[32:35], v[148:151], v[198:201], v[32:35]
	v_mfma_f32_16x16x32_bf16 v[32:35], v[152:155], v[208:211], v[32:35]
	v_mfma_f32_16x16x32_bf16 v[12:15], v[174:177], v[198:201], v[12:15]
	v_mfma_f32_16x16x32_bf16 v[12:15], v[178:181], v[208:211], v[12:15]
	v_mfma_f32_16x16x32_bf16 v[24:27], v[132:135], v[212:215], v[24:27]
	v_mfma_f32_16x16x32_bf16 v[24:27], v[136:139], v[216:219], v[24:27]
	v_mfma_f32_16x16x32_bf16 v[8:11], v[156:159], v[212:215], v[8:11]
	v_mfma_f32_16x16x32_bf16 v[8:11], v[170:173], v[216:219], v[8:11]
	v_mfma_f32_16x16x32_bf16 v[16:19], v[148:151], v[212:215], v[16:19]
	v_mfma_f32_16x16x32_bf16 v[16:19], v[152:155], v[216:219], v[16:19]
	v_mfma_f32_16x16x32_bf16 v[4:7], v[174:177], v[212:215], v[4:7]
	v_mfma_f32_16x16x32_bf16 v[4:7], v[178:181], v[216:219], v[4:7]
	s_setprio 0
	s_barrier
	s_add_i32 s69, s69, 2
	s_add_u32 s28, s28, 0x100
	s_addc_u32 s29, s29, 0
	s_add_u32 s63, s63, 0x100
	s_addc_u32 s68, s68, 0
	s_cmp_gt_u32 s69, 29
	s_cbranch_scc0 .LBB0_430
	s_and_b64 vcc, exec, s[8:9]
	s_cbranch_vccz .LBB0_433
	s_barrier

.LBB0_495:
	s_sleep 2
	s_add_u32 s22, s20, 0xfff80080
	s_addc_u32 s23, s21, -1
	s_add_i32 s48, 0, 0x10000
	s_cmp_eq_u32 s47, 28
	s_cselect_b32 s25, s15, s23
	s_cselect_b32 s24, s43, s22
	s_cselect_b32 s23, s11, s46
	s_cselect_b32 s22, s44, s45
	s_add_i32 s50, 0, 0x14000
	s_waitcnt lgkmcnt(0)
	v_add_u32_e32 v152, s48, v137
	v_add_u32_e32 v168, s50, v137
	ds_read_b128 v[140:143], v152
	ds_read_b128 v[144:147], v152 offset:1024
	ds_read_b128 v[148:151], v152 offset:2048
	ds_read_b128 v[152:155], v152 offset:3072
	ds_read_b128 v[156:159], v168
	ds_read_b128 v[160:163], v168 offset:1024
	ds_read_b128 v[164:167], v168 offset:2048
	ds_read_b128 v[168:171], v168 offset:3072
	v_lshl_add_u64 v[204:205], s[20:21], 0, v[132:133]
	s_add_i32 m0, s31, 0xc000
	ds_read_b128 v[172:175], v139
	ds_read_b128 v[176:179], v139 offset:1024
	ds_read_b128 v[180:183], v139 offset:2048
	ds_read_b128 v[184:187], v139 offset:3072
	ds_read_b128 v[188:191], v139 offset:4096
	ds_read_b128 v[192:195], v139 offset:5120
	ds_read_b128 v[196:199], v139 offset:6144
	ds_read_b128 v[200:203], v139 offset:7168
	global_load_lds_dwordx4 v[204:205], off
	v_lshl_add_u64 v[204:205], s[20:21], 0, v[134:135]
	s_add_i32 m0, s31, 0xe000
	s_nop 0
	global_load_lds_dwordx4 v[204:205], off
	s_waitcnt vmcnt(8)
	s_waitcnt lgkmcnt(0)
	s_barrier
	s_setprio 1
	s_waitcnt lgkmcnt(0)
	v_mfma_f32_16x16x32_bf16 v[128:131], v[140:143], v[172:175], v[128:131]
	v_mfma_f32_16x16x32_bf16 v[128:131], v[144:147], v[176:179], v[128:131]
	v_mfma_f32_16x16x32_bf16 v[112:115], v[156:159], v[172:175], v[112:115]
	v_mfma_f32_16x16x32_bf16 v[112:115], v[160:163], v[176:179], v[112:115]
	v_mfma_f32_16x16x32_bf16 v[124:127], v[148:151], v[172:175], v[124:127]
	v_mfma_f32_16x16x32_bf16 v[124:127], v[152:155], v[176:179], v[124:127]
	v_mfma_f32_16x16x32_bf16 v[104:107], v[164:167], v[172:175], v[104:107]
	v_mfma_f32_16x16x32_bf16 v[104:107], v[168:171], v[176:179], v[104:107]
	v_mfma_f32_16x16x32_bf16 v[120:123], v[140:143], v[180:183], v[120:123]
	v_mfma_f32_16x16x32_bf16 v[120:123], v[144:147], v[184:187], v[120:123]
	v_mfma_f32_16x16x32_bf16 v[96:99], v[156:159], v[180:183], v[96:99]
	v_mfma_f32_16x16x32_bf16 v[96:99], v[160:163], v[184:187], v[96:99]
	v_mfma_f32_16x16x32_bf16 v[116:119], v[148:151], v[180:183], v[116:119]
	v_mfma_f32_16x16x32_bf16 v[116:119], v[152:155], v[184:187], v[116:119]
	v_mfma_f32_16x16x32_bf16 v[88:91], v[164:167], v[180:183], v[88:91]
	v_mfma_f32_16x16x32_bf16 v[88:91], v[168:171], v[184:187], v[88:91]
	v_mfma_f32_16x16x32_bf16 v[108:111], v[140:143], v[188:191], v[108:111]
	v_mfma_f32_16x16x32_bf16 v[108:111], v[144:147], v[192:195], v[108:111]
	v_mfma_f32_16x16x32_bf16 v[80:83], v[156:159], v[188:191], v[80:83]
	v_mfma_f32_16x16x32_bf16 v[80:83], v[160:163], v[192:195], v[80:83]
	v_mfma_f32_16x16x32_bf16 v[100:103], v[148:151], v[188:191], v[100:103]
	v_mfma_f32_16x16x32_bf16 v[100:103], v[152:155], v[192:195], v[100:103]
	v_mfma_f32_16x16x32_bf16 v[76:79], v[164:167], v[188:191], v[76:79]
	v_mfma_f32_16x16x32_bf16 v[76:79], v[168:171], v[192:195], v[76:79]
	v_mfma_f32_16x16x32_bf16 v[92:95], v[140:143], v[196:199], v[92:95]
	v_mfma_f32_16x16x32_bf16 v[92:95], v[144:147], v[200:203], v[92:95]
	v_mfma_f32_16x16x32_bf16 v[72:75], v[156:159], v[196:199], v[72:75]
	v_mfma_f32_16x16x32_bf16 v[72:75], v[160:163], v[200:203], v[72:75]
	v_mfma_f32_16x16x32_bf16 v[84:87], v[148:151], v[196:199], v[84:87]
	v_mfma_f32_16x16x32_bf16 v[84:87], v[152:155], v[200:203], v[84:87]
	v_mfma_f32_16x16x32_bf16 v[68:71], v[164:167], v[196:199], v[68:71]
	v_mfma_f32_16x16x32_bf16 v[68:71], v[168:171], v[200:203], v[68:71]
	s_setprio 0
	s_barrier
	s_sleep 2
	s_add_i32 s48, s48, s0
	v_lshl_add_u64 v[204:205], s[22:23], 0, v[2:3]
	s_mov_b32 m0, s48
	ds_read_b128 v[172:175], v139 offset:16384
	ds_read_b128 v[176:179], v139 offset:17408
	ds_read_b128 v[180:183], v139 offset:18432
	ds_read_b128 v[184:187], v139 offset:19456
	ds_read_b128 v[188:191], v139 offset:20480
	ds_read_b128 v[192:195], v139 offset:21504
	ds_read_b128 v[196:199], v139 offset:22528
	ds_read_b128 v[200:203], v139 offset:23552
	global_load_lds_dwordx4 v[204:205], off
	s_add_i32 m0, s48, 0x2000
	s_add_u32 s48, s22, 0x80000
	v_lshl_add_u64 v[206:207], s[22:23], 0, v[0:1]
	s_addc_u32 s49, s23, 0
	s_add_i32 s50, s50, s0
	global_load_lds_dwordx4 v[206:207], off
	v_lshl_add_u64 v[208:209], s[48:49], 0, v[2:3]
	s_mov_b32 m0, s50
	v_lshl_add_u64 v[210:211], s[24:25], 0, v[0:1]
	global_load_lds_dwordx4 v[208:209], off
	v_lshl_add_u64 v[208:209], s[48:49], 0, v[0:1]
	s_add_i32 m0, s50, 0x2000
	s_nop 0
	global_load_lds_dwordx4 v[208:209], off
	v_lshl_add_u64 v[208:209], s[24:25], 0, v[2:3]
	s_mov_b32 m0, s31
	s_nop 0
	global_load_lds_dwordx4 v[208:209], off
	s_mov_b32 m0, s40
	s_nop 0
	global_load_lds_dwordx4 v[210:211], off
	s_waitcnt vmcnt(8)
	s_waitcnt lgkmcnt(0)
	s_barrier
	s_setprio 1
	s_waitcnt lgkmcnt(0)
	v_mfma_f32_16x16x32_bf16 v[64:67], v[140:143], v[172:175], v[64:67]
	v_mfma_f32_16x16x32_bf16 v[64:67], v[144:147], v[176:179], v[64:67]
	v_mfma_f32_16x16x32_bf16 v[48:51], v[156:159], v[172:175], v[48:51]
	v_mfma_f32_16x16x32_bf16 v[48:51], v[160:163], v[176:179], v[48:51]
	v_mfma_f32_16x16x32_bf16 v[60:63], v[148:151], v[172:175], v[60:63]
	v_mfma_f32_16x16x32_bf16 v[60:63], v[152:155], v[176:179], v[60:63]
	v_mfma_f32_16x16x32_bf16 v[44:47], v[164:167], v[172:175], v[44:47]
	v_mfma_f32_16x16x32_bf16 v[44:47], v[168:171], v[176:179], v[44:47]
	v_mfma_f32_16x16x32_bf16 v[56:59], v[140:143], v[180:183], v[56:59]
	v_mfma_f32_16x16x32_bf16 v[56:59], v[144:147], v[184:187], v[56:59]
	v_mfma_f32_16x16x32_bf16 v[32:35], v[156:159], v[180:183], v[32:35]
	v_mfma_f32_16x16x32_bf16 v[32:35], v[160:163], v[184:187], v[32:35]
	v_mfma_f32_16x16x32_bf16 v[52:55], v[148:151], v[180:183], v[52:55]
	v_mfma_f32_16x16x32_bf16 v[52:55], v[152:155], v[184:187], v[52:55]
	v_mfma_f32_16x16x32_bf16 v[28:31], v[164:167], v[180:183], v[28:31]
	v_mfma_f32_16x16x32_bf16 v[28:31], v[168:171], v[184:187], v[28:31]
	v_mfma_f32_16x16x32_bf16 v[40:43], v[140:143], v[188:191], v[40:43]
	v_mfma_f32_16x16x32_bf16 v[40:43], v[144:147], v[192:195], v[40:43]
	v_mfma_f32_16x16x32_bf16 v[16:19], v[156:159], v[188:191], v[16:19]
	v_mfma_f32_16x16x32_bf16 v[16:19], v[160:163], v[192:195], v[16:19]
	v_mfma_f32_16x16x32_bf16 v[36:39], v[148:151], v[188:191], v[36:39]
	v_mfma_f32_16x16x32_bf16 v[36:39], v[152:155], v[192:195], v[36:39]
	v_mfma_f32_16x16x32_bf16 v[12:15], v[164:167], v[188:191], v[12:15]
	v_mfma_f32_16x16x32_bf16 v[12:15], v[168:171], v[192:195], v[12:15]
	v_mfma_f32_16x16x32_bf16 v[24:27], v[140:143], v[196:199], v[24:27]
	v_mfma_f32_16x16x32_bf16 v[24:27], v[144:147], v[200:203], v[24:27]
	v_mfma_f32_16x16x32_bf16 v[8:11], v[156:159], v[196:199], v[8:11]
	v_mfma_f32_16x16x32_bf16 v[8:11], v[160:163], v[200:203], v[8:11]
	v_mfma_f32_16x16x32_bf16 v[20:23], v[148:151], v[196:199], v[20:23]
	v_mfma_f32_16x16x32_bf16 v[20:23], v[152:155], v[200:203], v[20:23]
	v_mfma_f32_16x16x32_bf16 v[4:7], v[164:167], v[196:199], v[4:7]
	v_mfma_f32_16x16x32_bf16 v[4:7], v[168:171], v[200:203], v[4:7]
	s_setprio 0
	s_barrier
	s_sleep 2
	s_add_i32 s48, 0, 0x18000
	s_add_i32 s49, 0, 0x1c000
	v_add_u32_e32 v152, s48, v137
	v_add_u32_e32 v168, s49, v137
	ds_read_b128 v[140:143], v152
	ds_read_b128 v[144:147], v152 offset:1024
	ds_read_b128 v[148:151], v152 offset:2048
	ds_read_b128 v[152:155], v152 offset:3072
	ds_read_b128 v[156:159], v168
	ds_read_b128 v[160:163], v168 offset:1024
	ds_read_b128 v[164:167], v168 offset:2048
	ds_read_b128 v[168:171], v168 offset:3072
	s_add_u32 s24, s24, 0x80000
	s_addc_u32 s25, s25, 0
	s_mov_b32 m0, s41
	v_lshl_add_u64 v[212:213], s[24:25], 0, v[2:3]
	ds_read_b128 v[172:175], v139 offset:32768
	ds_read_b128 v[176:179], v139 offset:33792
	ds_read_b128 v[180:183], v139 offset:34816
	ds_read_b128 v[184:187], v139 offset:35840
	ds_read_b128 v[188:191], v139 offset:36864
	ds_read_b128 v[192:195], v139 offset:37888
	ds_read_b128 v[196:199], v139 offset:38912
	ds_read_b128 v[200:203], v139 offset:39936
	global_load_lds_dwordx4 v[212:213], off
	v_lshl_add_u64 v[212:213], s[24:25], 0, v[0:1]
	s_mov_b32 m0, s42
	s_nop 0
	global_load_lds_dwordx4 v[212:213], off
	s_waitcnt vmcnt(8)
	s_waitcnt lgkmcnt(0)
	s_barrier
	s_setprio 1
	s_waitcnt lgkmcnt(0)
	v_mfma_f32_16x16x32_bf16 v[128:131], v[140:143], v[172:175], v[128:131]
	v_mfma_f32_16x16x32_bf16 v[128:131], v[144:147], v[176:179], v[128:131]
	v_mfma_f32_16x16x32_bf16 v[112:115], v[156:159], v[172:175], v[112:115]
	v_mfma_f32_16x16x32_bf16 v[112:115], v[160:163], v[176:179], v[112:115]
	v_mfma_f32_16x16x32_bf16 v[124:127], v[148:151], v[172:175], v[124:127]
	v_mfma_f32_16x16x32_bf16 v[124:127], v[152:155], v[176:179], v[124:127]
	v_mfma_f32_16x16x32_bf16 v[104:107], v[164:167], v[172:175], v[104:107]
	v_mfma_f32_16x16x32_bf16 v[104:107], v[168:171], v[176:179], v[104:107]
	v_mfma_f32_16x16x32_bf16 v[120:123], v[140:143], v[180:183], v[120:123]
	v_mfma_f32_16x16x32_bf16 v[120:123], v[144:147], v[184:187], v[120:123]
	v_mfma_f32_16x16x32_bf16 v[96:99], v[156:159], v[180:183], v[96:99]
	v_mfma_f32_16x16x32_bf16 v[96:99], v[160:163], v[184:187], v[96:99]
	v_mfma_f32_16x16x32_bf16 v[116:119], v[148:151], v[180:183], v[116:119]
	v_mfma_f32_16x16x32_bf16 v[116:119], v[152:155], v[184:187], v[116:119]
	v_mfma_f32_16x16x32_bf16 v[88:91], v[164:167], v[180:183], v[88:91]
	v_mfma_f32_16x16x32_bf16 v[88:91], v[168:171], v[184:187], v[88:91]
	v_mfma_f32_16x16x32_bf16 v[108:111], v[140:143], v[188:191], v[108:111]
	v_mfma_f32_16x16x32_bf16 v[108:111], v[144:147], v[192:195], v[108:111]
	v_mfma_f32_16x16x32_bf16 v[80:83], v[156:159], v[188:191], v[80:83]
	v_mfma_f32_16x16x32_bf16 v[80:83], v[160:163], v[192:195], v[80:83]
	v_mfma_f32_16x16x32_bf16 v[100:103], v[148:151], v[188:191], v[100:103]
	v_mfma_f32_16x16x32_bf16 v[100:103], v[152:155], v[192:195], v[100:103]
	v_mfma_f32_16x16x32_bf16 v[76:79], v[164:167], v[188:191], v[76:79]
	v_mfma_f32_16x16x32_bf16 v[76:79], v[168:171], v[192:195], v[76:79]
	v_mfma_f32_16x16x32_bf16 v[92:95], v[140:143], v[196:199], v[92:95]
	v_mfma_f32_16x16x32_bf16 v[92:95], v[144:147], v[200:203], v[92:95]
	v_mfma_f32_16x16x32_bf16 v[72:75], v[156:159], v[196:199], v[72:75]
	v_mfma_f32_16x16x32_bf16 v[72:75], v[160:163], v[200:203], v[72:75]
	v_mfma_f32_16x16x32_bf16 v[84:87], v[148:151], v[196:199], v[84:87]
	v_mfma_f32_16x16x32_bf16 v[84:87], v[152:155], v[200:203], v[84:87]
	v_mfma_f32_16x16x32_bf16 v[68:71], v[164:167], v[196:199], v[68:71]
	v_mfma_f32_16x16x32_bf16 v[68:71], v[168:171], v[200:203], v[68:71]
	s_setprio 0
	s_barrier
	s_sleep 2
	s_add_i32 s24, s48, s0
	v_lshl_add_u64 v[204:205], v[204:205], 0, s[66:67]
	s_mov_b32 m0, s24
	ds_read_b128 v[172:175], v139 offset:49152
	ds_read_b128 v[176:179], v139 offset:50176
	ds_read_b128 v[180:183], v139 offset:51200
	ds_read_b128 v[184:187], v139 offset:52224
	ds_read_b128 v[188:191], v139 offset:53248
	ds_read_b128 v[192:195], v139 offset:54272
	ds_read_b128 v[196:199], v139 offset:55296
	ds_read_b128 v[200:203], v139 offset:56320
	global_load_lds_dwordx4 v[204:205], off
	s_add_i32 m0, s24, 0x2000
	s_add_u32 s22, s22, 0x80080
	v_lshl_add_u64 v[204:205], v[206:207], 0, s[66:67]
	s_addc_u32 s23, s23, 0
	s_add_i32 s24, s49, s0
	global_load_lds_dwordx4 v[204:205], off
	v_lshl_add_u64 v[204:205], s[22:23], 0, v[2:3]
	s_mov_b32 m0, s24
	s_nop 0
	global_load_lds_dwordx4 v[204:205], off
	v_lshl_add_u64 v[204:205], s[22:23], 0, v[0:1]
	s_add_i32 m0, s24, 0x2000
	s_nop 0
	global_load_lds_dwordx4 v[204:205], off
	v_lshl_add_u64 v[204:205], v[208:209], 0, s[66:67]
	s_mov_b32 m0, s1
	s_nop 0
	global_load_lds_dwordx4 v[204:205], off
	v_lshl_add_u64 v[204:205], v[210:211], 0, s[66:67]
	s_mov_b32 m0, s34
	s_nop 0
	global_load_lds_dwordx4 v[204:205], off
	s_waitcnt vmcnt(8)
	s_waitcnt lgkmcnt(0)
	s_barrier
	s_setprio 1
	s_waitcnt lgkmcnt(0)
	v_mfma_f32_16x16x32_bf16 v[64:67], v[140:143], v[172:175], v[64:67]
	v_mfma_f32_16x16x32_bf16 v[64:67], v[144:147], v[176:179], v[64:67]
	v_mfma_f32_16x16x32_bf16 v[48:51], v[156:159], v[172:175], v[48:51]
	v_mfma_f32_16x16x32_bf16 v[48:51], v[160:163], v[176:179], v[48:51]
	v_mfma_f32_16x16x32_bf16 v[60:63], v[148:151], v[172:175], v[60:63]
	v_mfma_f32_16x16x32_bf16 v[60:63], v[152:155], v[176:179], v[60:63]
	v_mfma_f32_16x16x32_bf16 v[44:47], v[164:167], v[172:175], v[44:47]
	v_mfma_f32_16x16x32_bf16 v[44:47], v[168:171], v[176:179], v[44:47]
	v_mfma_f32_16x16x32_bf16 v[56:59], v[140:143], v[180:183], v[56:59]
	v_mfma_f32_16x16x32_bf16 v[56:59], v[144:147], v[184:187], v[56:59]
	v_mfma_f32_16x16x32_bf16 v[32:35], v[156:159], v[180:183], v[32:35]
	v_mfma_f32_16x16x32_bf16 v[32:35], v[160:163], v[184:187], v[32:35]
	v_mfma_f32_16x16x32_bf16 v[52:55], v[148:151], v[180:183], v[52:55]
	v_mfma_f32_16x16x32_bf16 v[52:55], v[152:155], v[184:187], v[52:55]
	v_mfma_f32_16x16x32_bf16 v[28:31], v[164:167], v[180:183], v[28:31]
	v_mfma_f32_16x16x32_bf16 v[28:31], v[168:171], v[184:187], v[28:31]
	v_mfma_f32_16x16x32_bf16 v[40:43], v[140:143], v[188:191], v[40:43]
	v_mfma_f32_16x16x32_bf16 v[40:43], v[144:147], v[192:195], v[40:43]
	v_mfma_f32_16x16x32_bf16 v[16:19], v[156:159], v[188:191], v[16:19]
	v_mfma_f32_16x16x32_bf16 v[16:19], v[160:163], v[192:195], v[16:19]
	v_mfma_f32_16x16x32_bf16 v[36:39], v[148:151], v[188:191], v[36:39]
	v_mfma_f32_16x16x32_bf16 v[36:39], v[152:155], v[192:195], v[36:39]
	v_mfma_f32_16x16x32_bf16 v[12:15], v[164:167], v[188:191], v[12:15]
	v_mfma_f32_16x16x32_bf16 v[12:15], v[168:171], v[192:195], v[12:15]
	v_mfma_f32_16x16x32_bf16 v[24:27], v[140:143], v[196:199], v[24:27]
	v_mfma_f32_16x16x32_bf16 v[24:27], v[144:147], v[200:203], v[24:27]
	v_mfma_f32_16x16x32_bf16 v[8:11], v[156:159], v[196:199], v[8:11]
	v_mfma_f32_16x16x32_bf16 v[8:11], v[160:163], v[200:203], v[8:11]
	v_mfma_f32_16x16x32_bf16 v[20:23], v[148:151], v[196:199], v[20:23]
	v_mfma_f32_16x16x32_bf16 v[20:23], v[152:155], v[200:203], v[20:23]
	v_mfma_f32_16x16x32_bf16 v[4:7], v[164:167], v[196:199], v[4:7]
	v_mfma_f32_16x16x32_bf16 v[4:7], v[168:171], v[200:203], v[4:7]
	s_setprio 0
	s_barrier
	s_add_i32 s47, s47, 2
	s_add_u32 s20, s20, 0x100
	s_addc_u32 s21, s21, 0
	s_add_u32 s45, s45, 0x100
	s_addc_u32 s46, s46, 0
	s_cmp_gt_u32 s47, 29
	s_cbranch_scc0 .LBB0_495
	s_and_b64 vcc, exec, s[8:9]
	s_cbranch_vccz .LBB0_498
	s_barrier

.LBB0_1010:
	s_sleep 2
	s_add_u32 s24, s22, 0xfff80080
	s_addc_u32 s25, s23, -1
	s_add_i32 s49, 0, 0x10000
	s_cmp_eq_u32 s48, 28
	s_cselect_b32 s27, s13, s25
	s_cselect_b32 s26, s19, s24
	s_cselect_b32 s25, s11, s47
	s_cselect_b32 s24, s45, s46
	s_add_i32 s52, 0, 0x14000
	v_add_u32_e32 v144, s49, v219
	v_add_u32_e32 v160, s52, v219
	ds_read_b128 v[116:119], v144
	ds_read_b128 v[124:127], v144 offset:1024
	ds_read_b128 v[132:135], v144 offset:2048
	ds_read_b128 v[144:147], v144 offset:3072
	ds_read_b128 v[148:151], v160
	ds_read_b128 v[152:155], v160 offset:1024
	ds_read_b128 v[156:159], v160 offset:2048
	ds_read_b128 v[160:163], v160 offset:3072
	v_lshl_add_u64 v[204:205], s[22:23], 0, v[192:193]
	s_add_i32 m0, s21, 0xc000
	ds_read_b128 v[164:167], v221
	ds_read_b128 v[168:171], v221 offset:1024
	ds_read_b128 v[172:175], v221 offset:2048
	ds_read_b128 v[176:179], v221 offset:3072
	ds_read_b128 v[180:183], v221 offset:4096
	ds_read_b128 v[184:187], v221 offset:5120
	ds_read_b128 v[196:199], v221 offset:6144
	ds_read_b128 v[200:203], v221 offset:7168
	global_load_lds_dwordx4 v[204:205], off
	v_lshl_add_u64 v[204:205], s[22:23], 0, v[194:195]
	s_add_i32 m0, s21, 0xe000
	s_nop 0
	global_load_lds_dwordx4 v[204:205], off
	s_waitcnt vmcnt(8)
	s_waitcnt lgkmcnt(0)
	s_barrier
	s_setprio 1
	s_waitcnt lgkmcnt(0)
	v_mfma_f32_16x16x32_bf16 v[140:143], v[116:119], v[164:167], v[140:143]
	v_mfma_f32_16x16x32_bf16 v[140:143], v[124:127], v[168:171], v[140:143]
	v_mfma_f32_16x16x32_bf16 v[128:131], v[148:151], v[164:167], v[128:131]
	v_mfma_f32_16x16x32_bf16 v[128:131], v[152:155], v[168:171], v[128:131]
	v_mfma_f32_16x16x32_bf16 v[136:139], v[132:135], v[164:167], v[136:139]
	v_mfma_f32_16x16x32_bf16 v[136:139], v[144:147], v[168:171], v[136:139]
	v_mfma_f32_16x16x32_bf16 v[120:123], v[156:159], v[164:167], v[120:123]
	v_mfma_f32_16x16x32_bf16 v[120:123], v[160:163], v[168:171], v[120:123]
	v_mfma_f32_16x16x32_bf16 v[112:115], v[116:119], v[172:175], v[112:115]
	v_mfma_f32_16x16x32_bf16 v[112:115], v[124:127], v[176:179], v[112:115]
	v_mfma_f32_16x16x32_bf16 v[104:107], v[148:151], v[172:175], v[104:107]
	v_mfma_f32_16x16x32_bf16 v[104:107], v[152:155], v[176:179], v[104:107]
	v_mfma_f32_16x16x32_bf16 v[108:111], v[132:135], v[172:175], v[108:111]
	v_mfma_f32_16x16x32_bf16 v[108:111], v[144:147], v[176:179], v[108:111]
	v_mfma_f32_16x16x32_bf16 v[100:103], v[156:159], v[172:175], v[100:103]
	v_mfma_f32_16x16x32_bf16 v[100:103], v[160:163], v[176:179], v[100:103]
	v_mfma_f32_16x16x32_bf16 v[96:99], v[116:119], v[180:183], v[96:99]
	v_mfma_f32_16x16x32_bf16 v[96:99], v[124:127], v[184:187], v[96:99]
	v_mfma_f32_16x16x32_bf16 v[88:91], v[148:151], v[180:183], v[88:91]
	v_mfma_f32_16x16x32_bf16 v[88:91], v[152:155], v[184:187], v[88:91]
	v_mfma_f32_16x16x32_bf16 v[92:95], v[132:135], v[180:183], v[92:95]
	v_mfma_f32_16x16x32_bf16 v[92:95], v[144:147], v[184:187], v[92:95]
	v_mfma_f32_16x16x32_bf16 v[84:87], v[156:159], v[180:183], v[84:87]
	v_mfma_f32_16x16x32_bf16 v[84:87], v[160:163], v[184:187], v[84:87]
	v_mfma_f32_16x16x32_bf16 v[80:83], v[116:119], v[196:199], v[80:83]
	v_mfma_f32_16x16x32_bf16 v[80:83], v[124:127], v[200:203], v[80:83]
	v_mfma_f32_16x16x32_bf16 v[72:75], v[148:151], v[196:199], v[72:75]
	v_mfma_f32_16x16x32_bf16 v[72:75], v[152:155], v[200:203], v[72:75]
	v_mfma_f32_16x16x32_bf16 v[76:79], v[132:135], v[196:199], v[76:79]
	v_mfma_f32_16x16x32_bf16 v[76:79], v[144:147], v[200:203], v[76:79]
	v_mfma_f32_16x16x32_bf16 v[68:71], v[156:159], v[196:199], v[68:71]
	v_mfma_f32_16x16x32_bf16 v[68:71], v[160:163], v[200:203], v[68:71]
	s_setprio 0
	s_barrier
	s_sleep 2
	s_add_i32 s49, s49, s30
	v_lshl_add_u64 v[204:205], s[24:25], 0, v[2:3]
	s_mov_b32 m0, s49
	ds_read_b128 v[164:167], v221 offset:16384
	ds_read_b128 v[168:171], v221 offset:17408
	ds_read_b128 v[172:175], v221 offset:18432
	ds_read_b128 v[176:179], v221 offset:19456
	ds_read_b128 v[180:183], v221 offset:20480
	ds_read_b128 v[184:187], v221 offset:21504
	ds_read_b128 v[196:199], v221 offset:22528
	ds_read_b128 v[200:203], v221 offset:23552
	global_load_lds_dwordx4 v[204:205], off
	s_add_i32 m0, s49, 0x2000
	s_add_u32 s50, s24, 0x80000
	v_lshl_add_u64 v[206:207], s[24:25], 0, v[190:191]
	s_addc_u32 s51, s25, 0
	s_add_i32 s49, s52, s30
	global_load_lds_dwordx4 v[206:207], off
	v_lshl_add_u64 v[208:209], s[50:51], 0, v[2:3]
	s_mov_b32 m0, s49
	v_lshl_add_u64 v[210:211], s[26:27], 0, v[188:189]
	global_load_lds_dwordx4 v[208:209], off
	v_lshl_add_u64 v[208:209], s[50:51], 0, v[190:191]
	s_add_i32 m0, s49, 0x2000
	s_nop 0
	global_load_lds_dwordx4 v[208:209], off
	v_lshl_add_u64 v[208:209], s[26:27], 0, v[0:1]
	s_mov_b32 m0, s21
	s_nop 0
	global_load_lds_dwordx4 v[208:209], off
	s_mov_b32 m0, s31
	s_nop 0
	global_load_lds_dwordx4 v[210:211], off
	s_waitcnt vmcnt(8)
	s_waitcnt lgkmcnt(0)
	s_barrier
	s_setprio 1
	s_waitcnt lgkmcnt(0)
	v_mfma_f32_16x16x32_bf16 v[64:67], v[116:119], v[164:167], v[64:67]
	v_mfma_f32_16x16x32_bf16 v[64:67], v[124:127], v[168:171], v[64:67]
	v_mfma_f32_16x16x32_bf16 v[56:59], v[148:151], v[164:167], v[56:59]
	v_mfma_f32_16x16x32_bf16 v[56:59], v[152:155], v[168:171], v[56:59]
	v_mfma_f32_16x16x32_bf16 v[60:63], v[132:135], v[164:167], v[60:63]
	v_mfma_f32_16x16x32_bf16 v[60:63], v[144:147], v[168:171], v[60:63]
	v_mfma_f32_16x16x32_bf16 v[52:55], v[156:159], v[164:167], v[52:55]
	v_mfma_f32_16x16x32_bf16 v[52:55], v[160:163], v[168:171], v[52:55]
	v_mfma_f32_16x16x32_bf16 v[48:51], v[116:119], v[172:175], v[48:51]
	v_mfma_f32_16x16x32_bf16 v[48:51], v[124:127], v[176:179], v[48:51]
	v_mfma_f32_16x16x32_bf16 v[40:43], v[148:151], v[172:175], v[40:43]
	v_mfma_f32_16x16x32_bf16 v[40:43], v[152:155], v[176:179], v[40:43]
	v_mfma_f32_16x16x32_bf16 v[44:47], v[132:135], v[172:175], v[44:47]
	v_mfma_f32_16x16x32_bf16 v[44:47], v[144:147], v[176:179], v[44:47]
	v_mfma_f32_16x16x32_bf16 v[36:39], v[156:159], v[172:175], v[36:39]
	v_mfma_f32_16x16x32_bf16 v[36:39], v[160:163], v[176:179], v[36:39]
	v_mfma_f32_16x16x32_bf16 v[32:35], v[116:119], v[180:183], v[32:35]
	v_mfma_f32_16x16x32_bf16 v[32:35], v[124:127], v[184:187], v[32:35]
	v_mfma_f32_16x16x32_bf16 v[24:27], v[148:151], v[180:183], v[24:27]
	v_mfma_f32_16x16x32_bf16 v[24:27], v[152:155], v[184:187], v[24:27]
	v_mfma_f32_16x16x32_bf16 v[28:31], v[132:135], v[180:183], v[28:31]
	v_mfma_f32_16x16x32_bf16 v[28:31], v[144:147], v[184:187], v[28:31]
	v_mfma_f32_16x16x32_bf16 v[20:23], v[156:159], v[180:183], v[20:23]
	v_mfma_f32_16x16x32_bf16 v[20:23], v[160:163], v[184:187], v[20:23]
	v_mfma_f32_16x16x32_bf16 v[16:19], v[116:119], v[196:199], v[16:19]
	v_mfma_f32_16x16x32_bf16 v[16:19], v[124:127], v[200:203], v[16:19]
	v_mfma_f32_16x16x32_bf16 v[8:11], v[148:151], v[196:199], v[8:11]
	v_mfma_f32_16x16x32_bf16 v[8:11], v[152:155], v[200:203], v[8:11]
	v_mfma_f32_16x16x32_bf16 v[12:15], v[132:135], v[196:199], v[12:15]
	v_mfma_f32_16x16x32_bf16 v[12:15], v[144:147], v[200:203], v[12:15]
	v_mfma_f32_16x16x32_bf16 v[4:7], v[156:159], v[196:199], v[4:7]
	v_mfma_f32_16x16x32_bf16 v[4:7], v[160:163], v[200:203], v[4:7]
	s_setprio 0
	s_barrier
	s_sleep 2
	s_add_i32 s49, 0, 0x18000
	s_add_i32 s50, 0, 0x1c000
	v_add_u32_e32 v144, s49, v219
	v_add_u32_e32 v160, s50, v219
	ds_read_b128 v[116:119], v144
	ds_read_b128 v[124:127], v144 offset:1024
	ds_read_b128 v[132:135], v144 offset:2048
	ds_read_b128 v[144:147], v144 offset:3072
	ds_read_b128 v[148:151], v160
	ds_read_b128 v[152:155], v160 offset:1024
	ds_read_b128 v[156:159], v160 offset:2048
	ds_read_b128 v[160:163], v160 offset:3072
	s_add_u32 s26, s26, 0x80000
	s_addc_u32 s27, s27, 0
	s_mov_b32 m0, s35
	v_lshl_add_u64 v[212:213], s[26:27], 0, v[0:1]
	ds_read_b128 v[164:167], v221 offset:32768
	ds_read_b128 v[168:171], v221 offset:33792
	ds_read_b128 v[172:175], v221 offset:34816
	ds_read_b128 v[176:179], v221 offset:35840
	ds_read_b128 v[180:183], v221 offset:36864
	ds_read_b128 v[184:187], v221 offset:37888
	ds_read_b128 v[196:199], v221 offset:38912
	ds_read_b128 v[200:203], v221 offset:39936
	global_load_lds_dwordx4 v[212:213], off
	v_lshl_add_u64 v[212:213], s[26:27], 0, v[188:189]
	s_mov_b32 m0, s40
	s_nop 0
	global_load_lds_dwordx4 v[212:213], off
	s_waitcnt vmcnt(8)
	s_waitcnt lgkmcnt(0)
	s_barrier
	s_setprio 1
	s_waitcnt lgkmcnt(0)
	v_mfma_f32_16x16x32_bf16 v[140:143], v[116:119], v[164:167], v[140:143]
	v_mfma_f32_16x16x32_bf16 v[140:143], v[124:127], v[168:171], v[140:143]
	v_mfma_f32_16x16x32_bf16 v[128:131], v[148:151], v[164:167], v[128:131]
	v_mfma_f32_16x16x32_bf16 v[128:131], v[152:155], v[168:171], v[128:131]
	v_mfma_f32_16x16x32_bf16 v[136:139], v[132:135], v[164:167], v[136:139]
	v_mfma_f32_16x16x32_bf16 v[136:139], v[144:147], v[168:171], v[136:139]
	v_mfma_f32_16x16x32_bf16 v[120:123], v[156:159], v[164:167], v[120:123]
	v_mfma_f32_16x16x32_bf16 v[120:123], v[160:163], v[168:171], v[120:123]
	v_mfma_f32_16x16x32_bf16 v[112:115], v[116:119], v[172:175], v[112:115]
	v_mfma_f32_16x16x32_bf16 v[112:115], v[124:127], v[176:179], v[112:115]
	v_mfma_f32_16x16x32_bf16 v[104:107], v[148:151], v[172:175], v[104:107]
	v_mfma_f32_16x16x32_bf16 v[104:107], v[152:155], v[176:179], v[104:107]
	v_mfma_f32_16x16x32_bf16 v[108:111], v[132:135], v[172:175], v[108:111]
	v_mfma_f32_16x16x32_bf16 v[108:111], v[144:147], v[176:179], v[108:111]
	v_mfma_f32_16x16x32_bf16 v[100:103], v[156:159], v[172:175], v[100:103]
	v_mfma_f32_16x16x32_bf16 v[100:103], v[160:163], v[176:179], v[100:103]
	v_mfma_f32_16x16x32_bf16 v[96:99], v[116:119], v[180:183], v[96:99]
	v_mfma_f32_16x16x32_bf16 v[96:99], v[124:127], v[184:187], v[96:99]
	v_mfma_f32_16x16x32_bf16 v[88:91], v[148:151], v[180:183], v[88:91]
	v_mfma_f32_16x16x32_bf16 v[88:91], v[152:155], v[184:187], v[88:91]
	v_mfma_f32_16x16x32_bf16 v[92:95], v[132:135], v[180:183], v[92:95]
	v_mfma_f32_16x16x32_bf16 v[92:95], v[144:147], v[184:187], v[92:95]
	v_mfma_f32_16x16x32_bf16 v[84:87], v[156:159], v[180:183], v[84:87]
	v_mfma_f32_16x16x32_bf16 v[84:87], v[160:163], v[184:187], v[84:87]
	v_mfma_f32_16x16x32_bf16 v[80:83], v[116:119], v[196:199], v[80:83]
	v_mfma_f32_16x16x32_bf16 v[80:83], v[124:127], v[200:203], v[80:83]
	v_mfma_f32_16x16x32_bf16 v[72:75], v[148:151], v[196:199], v[72:75]
	v_mfma_f32_16x16x32_bf16 v[72:75], v[152:155], v[200:203], v[72:75]
	v_mfma_f32_16x16x32_bf16 v[76:79], v[132:135], v[196:199], v[76:79]
	v_mfma_f32_16x16x32_bf16 v[76:79], v[144:147], v[200:203], v[76:79]
	v_mfma_f32_16x16x32_bf16 v[68:71], v[156:159], v[196:199], v[68:71]
	v_mfma_f32_16x16x32_bf16 v[68:71], v[160:163], v[200:203], v[68:71]
	s_setprio 0
	s_barrier
	s_sleep 2
	s_add_i32 s26, s49, s30
	v_lshl_add_u64 v[204:205], v[204:205], 0, s[66:67]
	s_mov_b32 m0, s26
	ds_read_b128 v[164:167], v221 offset:49152
	ds_read_b128 v[168:171], v221 offset:50176
	ds_read_b128 v[172:175], v221 offset:51200
	ds_read_b128 v[176:179], v221 offset:52224
	ds_read_b128 v[180:183], v221 offset:53248
	ds_read_b128 v[184:187], v221 offset:54272
	ds_read_b128 v[196:199], v221 offset:55296
	ds_read_b128 v[200:203], v221 offset:56320
	global_load_lds_dwordx4 v[204:205], off
	s_add_i32 m0, s26, 0x2000
	s_add_u32 s24, s24, 0x80080
	v_lshl_add_u64 v[204:205], v[206:207], 0, s[66:67]
	s_addc_u32 s25, s25, 0
	s_add_i32 s26, s50, s30
	global_load_lds_dwordx4 v[204:205], off
	v_lshl_add_u64 v[204:205], s[24:25], 0, v[2:3]
	s_mov_b32 m0, s26
	s_nop 0
	global_load_lds_dwordx4 v[204:205], off
	v_lshl_add_u64 v[204:205], s[24:25], 0, v[190:191]
	s_add_i32 m0, s26, 0x2000
	s_nop 0
	global_load_lds_dwordx4 v[204:205], off
	v_lshl_add_u64 v[204:205], v[208:209], 0, s[66:67]
	s_mov_b32 m0, s41
	s_nop 0
	global_load_lds_dwordx4 v[204:205], off
	v_lshl_add_u64 v[204:205], v[210:211], 0, s[66:67]
	s_mov_b32 m0, s42
	s_nop 0
	global_load_lds_dwordx4 v[204:205], off
	s_waitcnt vmcnt(8)
	s_waitcnt lgkmcnt(0)
	s_barrier
	s_setprio 1
	s_waitcnt lgkmcnt(0)
	v_mfma_f32_16x16x32_bf16 v[64:67], v[116:119], v[164:167], v[64:67]
	v_mfma_f32_16x16x32_bf16 v[64:67], v[124:127], v[168:171], v[64:67]
	v_mfma_f32_16x16x32_bf16 v[56:59], v[148:151], v[164:167], v[56:59]
	v_mfma_f32_16x16x32_bf16 v[56:59], v[152:155], v[168:171], v[56:59]
	v_mfma_f32_16x16x32_bf16 v[60:63], v[132:135], v[164:167], v[60:63]
	v_mfma_f32_16x16x32_bf16 v[60:63], v[144:147], v[168:171], v[60:63]
	v_mfma_f32_16x16x32_bf16 v[52:55], v[156:159], v[164:167], v[52:55]
	v_mfma_f32_16x16x32_bf16 v[52:55], v[160:163], v[168:171], v[52:55]
	v_mfma_f32_16x16x32_bf16 v[48:51], v[116:119], v[172:175], v[48:51]
	v_mfma_f32_16x16x32_bf16 v[48:51], v[124:127], v[176:179], v[48:51]
	v_mfma_f32_16x16x32_bf16 v[40:43], v[148:151], v[172:175], v[40:43]
	v_mfma_f32_16x16x32_bf16 v[40:43], v[152:155], v[176:179], v[40:43]
	v_mfma_f32_16x16x32_bf16 v[44:47], v[132:135], v[172:175], v[44:47]
	v_mfma_f32_16x16x32_bf16 v[44:47], v[144:147], v[176:179], v[44:47]
	v_mfma_f32_16x16x32_bf16 v[36:39], v[156:159], v[172:175], v[36:39]
	v_mfma_f32_16x16x32_bf16 v[36:39], v[160:163], v[176:179], v[36:39]
	v_mfma_f32_16x16x32_bf16 v[32:35], v[116:119], v[180:183], v[32:35]
	v_mfma_f32_16x16x32_bf16 v[32:35], v[124:127], v[184:187], v[32:35]
	v_mfma_f32_16x16x32_bf16 v[24:27], v[148:151], v[180:183], v[24:27]
	v_mfma_f32_16x16x32_bf16 v[24:27], v[152:155], v[184:187], v[24:27]
	v_mfma_f32_16x16x32_bf16 v[28:31], v[132:135], v[180:183], v[28:31]
	v_mfma_f32_16x16x32_bf16 v[28:31], v[144:147], v[184:187], v[28:31]
	v_mfma_f32_16x16x32_bf16 v[20:23], v[156:159], v[180:183], v[20:23]
	v_mfma_f32_16x16x32_bf16 v[20:23], v[160:163], v[184:187], v[20:23]
	v_mfma_f32_16x16x32_bf16 v[16:19], v[116:119], v[196:199], v[16:19]
	v_mfma_f32_16x16x32_bf16 v[16:19], v[124:127], v[200:203], v[16:19]
	v_mfma_f32_16x16x32_bf16 v[8:11], v[148:151], v[196:199], v[8:11]
	v_mfma_f32_16x16x32_bf16 v[8:11], v[152:155], v[200:203], v[8:11]
	v_mfma_f32_16x16x32_bf16 v[12:15], v[132:135], v[196:199], v[12:15]
	v_mfma_f32_16x16x32_bf16 v[12:15], v[144:147], v[200:203], v[12:15]
	v_mfma_f32_16x16x32_bf16 v[4:7], v[156:159], v[196:199], v[4:7]
	v_mfma_f32_16x16x32_bf16 v[4:7], v[160:163], v[200:203], v[4:7]
	s_setprio 0
	s_barrier
	s_add_i32 s48, s48, 2
	s_add_u32 s22, s22, 0x100
	s_addc_u32 s23, s23, 0
	s_add_u32 s46, s46, 0x100
	s_addc_u32 s47, s47, 0
	s_cmp_gt_u32 s48, 29
	s_cbranch_scc0 .LBB0_1010
	s_and_b64 vcc, exec, s[8:9]
	s_cbranch_vccz .LBB0_1013
	s_barrier
